# lever 7: LRU pass-1 lane-half exchange by v_permlane32_swap instead of ds_bpermute (4 sites x 8)
# speedup vs baseline: 1.0046x; 1.0046x over previous
; #define LAS __attribute__((address_space(3)))
; __device__ __forceinline__ float bf_lo(unsigned w) { return __uint_as_float(w << 16); }
; __device__ __forceinline__ float bf_hi(unsigned w) { return __uint_as_float(w & 0xffff0000u); }
; #define LDS_WAIT() asm volatile("s_waitcnt lgkmcnt(0)" ::: "memory")
; template <int PASS>
; __device__ __forceinline__ void lru_item(Frame& F, const LAS bf16* lw, const LAS float* prm, const LAS float* cwl, LAS float* xs, LAS unsigned char* pf, int head, int item, int nitem) {
;     ...
;     u32x4 vw[4][4];
; #pragma unroll
;     for (int k = 0; k < 4; ++k) {
;         const int rr = r - 1 + k; const bool ok = (rr >= 0) && (rr < 256);
;         const int row = t + k;
; #pragma unroll
;         for (int ks = 0; ks < 4; ++ks) { u32x4 w = *(const LAS u32x4*)(pf + row * 128 + (((2 * ks + hh) ^ ((row >> 1) & 7)) * 16)); if (!ok) w = (u32x4){0u, 0u, 0u, 0u}; vw[k][ks] = w; }
;     }
;     LDS_WAIT(); asm volatile("" ::: "memory");
;     if (nitem >= 0) lru_prefetch(F.ws, pf, lane, head, nitem);
;     float lc[2][2]; u32x4 gq[4];
;     const size_t tok = (size_t)b * SEQ + (size_t)r * 64 + col;
;     if (PASS == 2) {
; #pragma unroll
;         for (int d = 0; d < 2; ++d)
; #pragma unroll
;             for (int ct = 0; ct < 2; ++ct) lc[d][ct] = ((const float*)(F.ws + WS_LC))[(size_t)((b * 2 + d) * NQ + q) * 1024 + head * 64 + t + 32 * ct];
;     }
;     float xa[4][8];
; #pragma unroll
;     for (int ks = 0; ks < 4; ++ks) {
;         const int ch = 16 * ks + 8 * hh;
;         const f32x4 b0 = *(const LAS f32x4*)(cwl + 4 * 64 + ch), b1 = *(const LAS f32x4*)(cwl + 4 * 64 + ch + 4);
; #pragma unroll
;         for (int j = 0; j < 4; ++j) { xa[ks][j] = b0[j]; xa[ks][4 + j] = b1[j]; }
;     }
; #pragma unroll
;     for (int k = 0; k < 4; ++k)
; #pragma unroll
;         for (int ks = 0; ks < 4; ++ks) {
;             const u32x4 w = vw[k][ks]; const int ch = 16 * ks + 8 * hh;
;             const f32x4 c0 = *(const LAS f32x4*)(cwl + k * 64 + ch), c1 = *(const LAS f32x4*)(cwl + k * 64 + ch + 4);
;             xa[ks][0] += c0[0] * bf_lo(w.x); xa[ks][1] += c0[1] * bf_hi(w.x); xa[ks][2] += c0[2] * bf_lo(w.y); xa[ks][3] += c0[3] * bf_hi(w.y);
;             xa[ks][4] += c1[0] * bf_lo(w.z); xa[ks][5] += c1[1] * bf_hi(w.z); xa[ks][6] += c1[2] * bf_lo(w.w); xa[ks][7] += c1[3] * bf_hi(w.w);
;         }
.LBB0_702:
	v_add_u32_e32 v64, s18, v110
	v_cmp_gt_u32_e32 vcc, s42, v64
	v_and_b32_e32 v88, 0xffffffe0, v111
	v_add_u32_e32 v124, 0, v88
	s_waitcnt lgkmcnt(0)
	v_cndmask_b32_e32 v125, 0, v21, vcc
	v_cndmask_b32_e32 v166, 0, v20, vcc
	v_cndmask_b32_e32 v84, 0, v23, vcc
	v_cndmask_b32_e32 v85, 0, v22, vcc
	v_cndmask_b32_e32 v167, 0, v9, vcc
	v_cndmask_b32_e32 v168, 0, v8, vcc
	v_cndmask_b32_e32 v90, 0, v11, vcc
	v_cndmask_b32_e32 v91, 0, v10, vcc
	v_cndmask_b32_e32 v169, 0, v25, vcc
	v_cndmask_b32_e32 v170, 0, v24, vcc
	v_cndmask_b32_e32 v92, 0, v27, vcc
	v_cndmask_b32_e32 v93, 0, v26, vcc
	v_cndmask_b32_e32 v117, 0, v17, vcc
	v_cndmask_b32_e32 v120, 0, v16, vcc
	v_cndmask_b32_e32 v134, 0, v19, vcc
	v_cndmask_b32_e32 v135, 0, v18, vcc
	v_cmp_eq_u32_e32 vcc, s49, v64
	v_add_u32_e32 v8, 3, v64
	v_lshlrev_b32_e32 v81, 16, v30
	v_cndmask_b32_e64 v171, v63, 0, vcc
	v_cndmask_b32_e64 v172, v62, 0, vcc
	v_cndmask_b32_e64 v173, v61, 0, vcc
	v_cndmask_b32_e64 v174, v60, 0, vcc
	v_cndmask_b32_e64 v175, v47, 0, vcc
	v_cndmask_b32_e64 v176, v46, 0, vcc
	v_cndmask_b32_e64 v177, v45, 0, vcc
	v_cndmask_b32_e64 v178, v44, 0, vcc
	v_cndmask_b32_e64 v123, v55, 0, vcc
	v_cndmask_b32_e64 v179, v54, 0, vcc
	v_cndmask_b32_e64 v180, v53, 0, vcc
	v_cndmask_b32_e64 v181, v52, 0, vcc
	v_cndmask_b32_e64 v113, v39, 0, vcc
	v_cndmask_b32_e64 v115, v38, 0, vcc
	v_cndmask_b32_e64 v118, v37, 0, vcc
	v_cndmask_b32_e64 v121, v36, 0, vcc
	v_cmp_gt_u32_e32 vcc, s42, v8
	v_lshlrev_b32_e32 v80, 16, v85
	s_ashr_i32 s4, s62, 3
	v_cndmask_b32_e32 v182, 0, v59, vcc
	v_cndmask_b32_e32 v183, 0, v58, vcc
	v_cndmask_b32_e32 v184, 0, v57, vcc
	v_cndmask_b32_e32 v185, 0, v56, vcc
	v_cndmask_b32_e32 v186, 0, v43, vcc
	v_cndmask_b32_e32 v187, 0, v42, vcc
	v_cndmask_b32_e32 v188, 0, v41, vcc
	v_cndmask_b32_e32 v189, 0, v40, vcc
	v_cndmask_b32_e32 v190, 0, v51, vcc
	v_cndmask_b32_e32 v191, 0, v50, vcc
	v_cndmask_b32_e32 v192, 0, v49, vcc
	v_cndmask_b32_e32 v193, 0, v48, vcc
	v_cndmask_b32_e32 v114, 0, v35, vcc
	v_cndmask_b32_e32 v116, 0, v34, vcc
	v_cndmask_b32_e32 v119, 0, v33, vcc
	v_cndmask_b32_e32 v122, 0, v32, vcc
	ds_read_b128 v[36:39], v124 offset:39424
	ds_read_b128 v[52:55], v124 offset:39440
	ds_read_b128 v[64:67], v124 offset:39488
	ds_read_b128 v[60:63], v124 offset:39504
	ds_read_b128 v[44:47], v124 offset:39552
	ds_read_b128 v[24:27], v124 offset:39568
	ds_read_b128 v[16:19], v124 offset:39616
	ds_read_b128 v[8:11], v124 offset:39632
	ds_read_b128 v[126:129], v124 offset:38400
	ds_read_b128 v[32:35], v124 offset:38416
	ds_read_b128 v[76:79], v124 offset:38464
	ds_read_b128 v[40:43], v124 offset:38480
	ds_read_b128 v[48:51], v124 offset:38528
	ds_read_b128 v[56:59], v124 offset:38544
	ds_read_b128 v[130:133], v124 offset:38656
	ds_read_b128 v[68:71], v124 offset:38672
	ds_read_b128 v[20:23], v124 offset:38592
	ds_read_b128 v[72:75], v124 offset:38608
	s_waitcnt lgkmcnt(0)
	v_mov_b32_e32 v82, v32
	v_lshlrev_b32_e32 v32, 16, v84
	v_mov_b32_e32 v83, v68
	v_pk_mul_f32 v[158:159], v[82:83], v[80:81]
	v_and_b32_e32 v81, 0xffff0000, v30
	v_and_b32_e32 v80, 0xffff0000, v85
	v_mov_b32_e32 v68, v33
	v_pk_mul_f32 v[160:161], v[68:69], v[80:81]
	v_lshlrev_b32_e32 v33, 16, v31
	v_mov_b32_e32 v68, v34
	v_mov_b32_e32 v69, v70
	v_pk_mul_f32 v[162:163], v[68:69], v[32:33]
	v_and_b32_e32 v69, 0xffff0000, v31
	v_and_b32_e32 v68, 0xffff0000, v84
	ds_read_b128 v[84:87], v124 offset:38720
	ds_read_b128 v[30:33], v124 offset:38736
	v_mov_b32_e32 v70, v35
	v_pk_mul_f32 v[164:165], v[70:71], v[68:69]
	v_lshlrev_b32_e32 v35, 16, v14
	v_lshlrev_b32_e32 v34, 16, v91
	v_mov_b32_e32 v68, v40
	s_waitcnt lgkmcnt(0)
	v_mov_b32_e32 v69, v30
	v_pk_mul_f32 v[104:105], v[68:69], v[34:35]
	ds_read_b128 v[68:71], v124 offset:38784
	ds_read_b128 v[80:83], v124 offset:38800
	v_and_b32_e32 v35, 0xffff0000, v14
	v_and_b32_e32 v34, 0xffff0000, v91
	v_mov_b32_e32 v30, v41
	v_pk_mul_f32 v[106:107], v[30:31], v[34:35]
	v_lshlrev_b32_e32 v31, 16, v15
	v_lshlrev_b32_e32 v30, 16, v90
	v_mov_b32_e32 v34, v42
	v_mov_b32_e32 v35, v32
	v_and_b32_e32 v15, 0xffff0000, v15
	v_and_b32_e32 v14, 0xffff0000, v90
	v_mov_b32_e32 v32, v43
	v_pk_mul_f32 v[102:103], v[34:35], v[30:31]
	v_pk_mul_f32 v[14:15], v[32:33], v[14:15]
	v_lshlrev_b32_e32 v31, 16, v6
	v_lshlrev_b32_e32 v30, 16, v93
	v_mov_b32_e32 v32, v56
	s_waitcnt lgkmcnt(0)
	v_mov_b32_e32 v33, v80
	v_pk_mul_f32 v[98:99], v[32:33], v[30:31]
	v_and_b32_e32 v31, 0xffff0000, v6
	v_and_b32_e32 v30, 0xffff0000, v93
	v_mov_b32_e32 v80, v57
	v_pk_mul_f32 v[100:101], v[80:81], v[30:31]
	v_lshlrev_b32_e32 v31, 16, v7
	v_lshlrev_b32_e32 v30, 16, v92
	v_mov_b32_e32 v32, v58
	v_mov_b32_e32 v33, v82
	v_pk_mul_f32 v[94:95], v[32:33], v[30:31]
	ds_read_b128 v[40:43], v124 offset:38848
	ds_read_b128 v[30:33], v124 offset:38864
	v_and_b32_e32 v7, 0xffff0000, v7
	v_and_b32_e32 v6, 0xffff0000, v92
	v_mov_b32_e32 v82, v59
	v_pk_mul_f32 v[96:97], v[82:83], v[6:7]
	v_lshlrev_b32_e32 v7, 16, v2
	v_lshlrev_b32_e32 v6, 16, v135
	v_mov_b32_e32 v34, v72
	s_waitcnt lgkmcnt(0)
	v_mov_b32_e32 v35, v30
	v_pk_mul_f32 v[90:91], v[34:35], v[6:7]
	v_and_b32_e32 v7, 0xffff0000, v2
	v_and_b32_e32 v6, 0xffff0000, v135
	v_mov_b32_e32 v30, v73
	v_pk_mul_f32 v[92:93], v[30:31], v[6:7]
	v_lshlrev_b32_e32 v7, 16, v3
	v_lshlrev_b32_e32 v6, 16, v134
	v_mov_b32_e32 v30, v74
	v_mov_b32_e32 v31, v32
	v_and_b32_e32 v3, 0xffff0000, v3
	v_and_b32_e32 v2, 0xffff0000, v134
	v_mov_b32_e32 v32, v75
	v_pk_mul_f32 v[6:7], v[30:31], v[6:7]
	v_pk_mul_f32 v[34:35], v[32:33], v[2:3]
	ds_read_b128 v[134:137], v124 offset:38912
	ds_read_b128 v[138:141], v124 offset:38928
	ds_read_b128 v[142:145], v124 offset:38976
	ds_read_b128 v[146:149], v124 offset:38992
	ds_read_b128 v[80:83], v124 offset:39040
	ds_read_b128 v[72:75], v124 offset:39056
	ds_read_b128 v[56:59], v124 offset:39104
	ds_read_b128 v[30:33], v124 offset:39120
	ds_read_b128 v[150:153], v124 offset:39168
	ds_read_b128 v[154:157], v124 offset:39184
	v_lshlrev_b32_e32 v2, 16, v166
	v_and_b32_e32 v3, 0xffff0000, v166
	v_pk_fma_f32 v[2:3], v[126:127], v[2:3], v[36:37]
	v_lshlrev_b32_e32 v36, 16, v28
	v_and_b32_e32 v37, 0xffff0000, v28
	v_pk_fma_f32 v[2:3], v[130:131], v[36:37], v[2:3]
	v_lshlrev_b32_e32 v36, 16, v174
	v_and_b32_e32 v37, 0xffff0000, v174
	s_waitcnt lgkmcnt(0)
; #define LAS __attribute__((address_space(3)))
; __device__ __forceinline__ float bf_lo(unsigned w) { return __uint_as_float(w << 16); }
; __device__ __forceinline__ float bf_hi(unsigned w) { return __uint_as_float(w & 0xffff0000u); }
; template <int PASS>
; __device__ __forceinline__ void lru_item(Frame& F, const LAS bf16* lw, const LAS float* prm, const LAS float* cwl, LAS float* xs, LAS unsigned char* pf, int head, int item, int nitem) {
;     ...
; #pragma unroll
;     for (int k = 0; k < 4; ++k)
; #pragma unroll
;         for (int ks = 0; ks < 4; ++ks) {
;             const u32x4 w = vw[k][ks]; const int ch = 16 * ks + 8 * hh;
;             const f32x4 c0 = *(const LAS f32x4*)(cwl + k * 64 + ch), c1 = *(const LAS f32x4*)(cwl + k * 64 + ch + 4);
;             xa[ks][0] += c0[0] * bf_lo(w.x); xa[ks][1] += c0[1] * bf_hi(w.x); xa[ks][2] += c0[2] * bf_lo(w.y); xa[ks][3] += c0[3] * bf_hi(w.y);
;             xa[ks][4] += c1[0] * bf_lo(w.z); xa[ks][5] += c1[1] * bf_hi(w.z); xa[ks][6] += c1[2] * bf_lo(w.w); xa[ks][7] += c1[3] * bf_hi(w.w);
;         }
	v_pk_fma_f32 v[2:3], v[134:135], v[36:37], v[2:3]
	v_lshlrev_b32_e32 v36, 16, v185
	v_and_b32_e32 v37, 0xffff0000, v185
	v_pk_fma_f32 v[36:37], v[150:151], v[36:37], v[2:3]
	v_lshlrev_b32_e32 v2, 16, v125
	v_and_b32_e32 v3, 0xffff0000, v125
	v_pk_fma_f32 v[2:3], v[128:129], v[2:3], v[38:39]
	v_lshlrev_b32_e32 v28, 16, v29
	v_and_b32_e32 v29, 0xffff0000, v29
	v_pk_fma_f32 v[2:3], v[132:133], v[28:29], v[2:3]
	v_lshlrev_b32_e32 v28, 16, v173
	v_and_b32_e32 v29, 0xffff0000, v173
	v_pk_fma_f32 v[2:3], v[136:137], v[28:29], v[2:3]
	v_lshlrev_b32_e32 v28, 16, v184
	v_and_b32_e32 v29, 0xffff0000, v184
	v_pk_fma_f32 v[38:39], v[152:153], v[28:29], v[2:3]
	v_lshlrev_b32_e32 v2, 16, v172
	v_lshlrev_b32_e32 v3, 16, v183
	v_mov_b32_e32 v28, v138
	v_mov_b32_e32 v29, v154
	v_pk_mul_f32 v[2:3], v[28:29], v[2:3]
	v_and_b32_e32 v29, 0xffff0000, v183
	v_and_b32_e32 v28, 0xffff0000, v172
	v_mov_b32_e32 v154, v139
	v_mov_b32_e32 v126, v158
	v_mov_b32_e32 v127, v160
	v_pk_mul_f32 v[28:29], v[154:155], v[28:29]
	v_pk_add_f32 v[52:53], v[52:53], v[126:127]
	v_mov_b32_e32 v160, v159
	v_pk_add_f32 v[52:53], v[52:53], v[160:161]
	v_mov_b32_e32 v126, v2
	v_mov_b32_e32 v127, v28
	v_pk_add_f32 v[52:53], v[52:53], v[126:127]
	v_mov_b32_e32 v28, v3
	v_pk_add_f32 v[52:53], v[52:53], v[28:29]
	v_lshlrev_b32_e32 v2, 16, v171
	v_lshlrev_b32_e32 v3, 16, v182
	v_mov_b32_e32 v28, v140
	v_mov_b32_e32 v29, v156
	v_pk_mul_f32 v[2:3], v[28:29], v[2:3]
	v_and_b32_e32 v29, 0xffff0000, v182
	v_and_b32_e32 v28, 0xffff0000, v171
	v_mov_b32_e32 v156, v141
	v_mov_b32_e32 v126, v162
	v_mov_b32_e32 v127, v164
	v_pk_mul_f32 v[28:29], v[156:157], v[28:29]
	v_pk_add_f32 v[54:55], v[54:55], v[126:127]
	v_mov_b32_e32 v164, v163
	v_pk_add_f32 v[54:55], v[54:55], v[164:165]
	v_mov_b32_e32 v126, v2
	v_mov_b32_e32 v127, v28
	v_pk_add_f32 v[54:55], v[54:55], v[126:127]
	v_mov_b32_e32 v28, v3
	ds_read_b128 v[126:129], v124 offset:39232
	ds_read_b128 v[130:133], v124 offset:39248
	v_lshlrev_b32_e32 v2, 16, v168
	v_and_b32_e32 v3, 0xffff0000, v168
	v_pk_add_f32 v[54:55], v[54:55], v[28:29]
	v_pk_fma_f32 v[2:3], v[76:77], v[2:3], v[64:65]
	v_lshlrev_b32_e32 v28, 16, v12
	v_and_b32_e32 v29, 0xffff0000, v12
	v_pk_fma_f32 v[2:3], v[84:85], v[28:29], v[2:3]
	v_lshlrev_b32_e32 v28, 16, v178
	v_and_b32_e32 v29, 0xffff0000, v178
	v_pk_fma_f32 v[2:3], v[142:143], v[28:29], v[2:3]
	v_lshlrev_b32_e32 v28, 16, v189
	v_and_b32_e32 v29, 0xffff0000, v189
	s_waitcnt lgkmcnt(0)
	v_pk_fma_f32 v[64:65], v[126:127], v[28:29], v[2:3]
	v_lshlrev_b32_e32 v2, 16, v167
	v_and_b32_e32 v3, 0xffff0000, v167
	v_pk_fma_f32 v[2:3], v[78:79], v[2:3], v[66:67]
	v_lshlrev_b32_e32 v12, 16, v13
	v_and_b32_e32 v13, 0xffff0000, v13
	v_pk_fma_f32 v[2:3], v[86:87], v[12:13], v[2:3]
	v_lshlrev_b32_e32 v12, 16, v177
	v_and_b32_e32 v13, 0xffff0000, v177
	v_pk_fma_f32 v[2:3], v[144:145], v[12:13], v[2:3]
	v_lshlrev_b32_e32 v12, 16, v188
	v_and_b32_e32 v13, 0xffff0000, v188
	v_pk_fma_f32 v[66:67], v[128:129], v[12:13], v[2:3]
	v_lshlrev_b32_e32 v2, 16, v176
	v_lshlrev_b32_e32 v3, 16, v187
	v_mov_b32_e32 v12, v146
	v_mov_b32_e32 v13, v130
	v_pk_mul_f32 v[2:3], v[12:13], v[2:3]
	v_and_b32_e32 v13, 0xffff0000, v187
	v_and_b32_e32 v12, 0xffff0000, v176
	v_mov_b32_e32 v130, v147
	v_mov_b32_e32 v28, v104
	v_mov_b32_e32 v29, v106
	v_pk_mul_f32 v[12:13], v[130:131], v[12:13]
	v_pk_add_f32 v[28:29], v[60:61], v[28:29]
	v_mov_b32_e32 v106, v105
	v_pk_add_f32 v[28:29], v[28:29], v[106:107]
	v_mov_b32_e32 v60, v2
	v_mov_b32_e32 v61, v12
	v_pk_add_f32 v[28:29], v[28:29], v[60:61]
	v_mov_b32_e32 v12, v3
	v_pk_add_f32 v[12:13], v[28:29], v[12:13]
	v_lshlrev_b32_e32 v2, 16, v175
	v_lshlrev_b32_e32 v3, 16, v186
	v_mov_b32_e32 v28, v148
	v_mov_b32_e32 v29, v132
	v_pk_mul_f32 v[2:3], v[28:29], v[2:3]
	v_and_b32_e32 v29, 0xffff0000, v186
	v_and_b32_e32 v28, 0xffff0000, v175
	v_mov_b32_e32 v132, v149
	v_mov_b32_e32 v60, v102
	v_mov_b32_e32 v61, v14
	v_pk_mul_f32 v[28:29], v[132:133], v[28:29]
	v_pk_add_f32 v[60:61], v[62:63], v[60:61]
	v_mov_b32_e32 v14, v103
	v_pk_add_f32 v[14:15], v[60:61], v[14:15]
	v_mov_b32_e32 v60, v2
	v_mov_b32_e32 v61, v28
	v_pk_add_f32 v[14:15], v[14:15], v[60:61]
	v_mov_b32_e32 v28, v3
	ds_read_b128 v[60:63], v124 offset:39296
	ds_read_b128 v[76:79], v124 offset:39312
	v_lshlrev_b32_e32 v2, 16, v170
	v_and_b32_e32 v3, 0xffff0000, v170
	v_pk_add_f32 v[14:15], v[14:15], v[28:29]
	v_pk_fma_f32 v[2:3], v[48:49], v[2:3], v[44:45]
	v_lshlrev_b32_e32 v28, 16, v4
	v_and_b32_e32 v29, 0xffff0000, v4
	v_pk_fma_f32 v[2:3], v[68:69], v[28:29], v[2:3]
	v_lshlrev_b32_e32 v28, 16, v181
	v_and_b32_e32 v29, 0xffff0000, v181
	v_pk_fma_f32 v[2:3], v[80:81], v[28:29], v[2:3]
	v_lshlrev_b32_e32 v28, 16, v193
	v_and_b32_e32 v29, 0xffff0000, v193
	s_waitcnt lgkmcnt(0)
; #define LAS __attribute__((address_space(3)))
; __device__ __forceinline__ unsigned cvt_pk_bf16(float lo, float hi) { unsigned r; asm volatile("v_cvt_pk_bf16_f32 %0, %1, %2" : "=v"(r) : "v"(lo), "v"(hi)); return r; }
; #define LDS_WAIT() asm volatile("s_waitcnt lgkmcnt(0)" ::: "memory")
; template <int PASS>
; __device__ __forceinline__ void lru_item(Frame& F, const LAS bf16* lw, const LAS float* prm, const LAS float* cwl, LAS float* xs, LAS unsigned char* pf, int head, int item, int nitem) {
;     ...
;     bf16x8 af[4];
; #pragma unroll
;     for (int ks = 0; ks < 4; ++ks) {
;         u32x4 w; w.x = cvt_pk_bf16(xa[ks][0], xa[ks][1]); w.y = cvt_pk_bf16(xa[ks][2], xa[ks][3]); w.z = cvt_pk_bf16(xa[ks][4], xa[ks][5]); w.w = cvt_pk_bf16(xa[ks][6], xa[ks][7]);
;         af[ks] = __builtin_bit_cast(bf16x8, w);
;         *(LAS f32x4*)(xs + t * 68 + 16 * ks + 8 * hh) = (f32x4){xa[ks][0], xa[ks][1], xa[ks][2], xa[ks][3]};
;         *(LAS f32x4*)(xs + t * 68 + 16 * ks + 8 * hh + 4) = (f32x4){xa[ks][4], xa[ks][5], xa[ks][6], xa[ks][7]};
;     }
;     if (PASS == 2) {
; #pragma unroll
;         for (int ks = 0; ks < 4; ++ks) gq[ks] = *(const u32x4*)((const bf16*)(F.ws + WS_GG) + tok * LRUW + head * 64 + 16 * ks + 8 * hh);
;     }
;     LDS_WAIT(); asm volatile("" ::: "memory");
;     float xd[2][16];
; #pragma unroll
;     for (int ct = 0; ct < 2; ++ct)
; #pragma unroll
;         for (int rg = 0; rg < 16; ++rg) xd[ct][rg] = xs[((rg & 3) + 8 * (rg >> 2) + 4 * hh) * 68 + t + 32 * ct];
;     float ysum[2][16];
; #pragma unroll
;     for (int d = 0; d < 2; ++d) {
; #pragma unroll
;         for (int ct = 0; ct < 2; ++ct) {
;             f32x16 acc[2];
; #pragma unroll
;             for (int gt = 0; gt < 2; ++gt) {
;                 f32x16 a; for (int i = 0; i < 16; ++i) a[i] = 0.f;
;                 const LAS bf16* wb = lw + ((d * 2 + gt) * 64 + t + 32 * ct) * LRU_WROW + 8 * hh;
; #pragma unroll
;                 for (int ks = 0; ks < 4; ++ks) a = __builtin_amdgcn_mfma_f32_32x32x16_bf16(af[ks], *(const LAS bf16x8*)(wb + 16 * ks), a, 0, 0, 0);
	v_pk_fma_f32 v[2:3], v[60:61], v[28:29], v[2:3]
	v_lshlrev_b32_e32 v28, 16, v169
	v_and_b32_e32 v29, 0xffff0000, v169
	v_pk_fma_f32 v[28:29], v[50:51], v[28:29], v[46:47]
	v_lshlrev_b32_e32 v4, 16, v5
	v_and_b32_e32 v5, 0xffff0000, v5
	v_pk_fma_f32 v[4:5], v[70:71], v[4:5], v[28:29]
	v_lshlrev_b32_e32 v28, 16, v180
	v_and_b32_e32 v29, 0xffff0000, v180
	v_pk_fma_f32 v[4:5], v[82:83], v[28:29], v[4:5]
	v_lshlrev_b32_e32 v28, 16, v192
	v_and_b32_e32 v29, 0xffff0000, v192
	v_pk_fma_f32 v[4:5], v[62:63], v[28:29], v[4:5]
	v_lshlrev_b32_e32 v28, 16, v179
	v_lshlrev_b32_e32 v29, 16, v191
	v_mov_b32_e32 v44, v72
	v_mov_b32_e32 v45, v76
	v_pk_mul_f32 v[28:29], v[44:45], v[28:29]
	v_and_b32_e32 v45, 0xffff0000, v191
	v_and_b32_e32 v44, 0xffff0000, v179
	v_mov_b32_e32 v76, v73
	v_mov_b32_e32 v46, v98
	v_mov_b32_e32 v47, v100
	v_pk_mul_f32 v[44:45], v[76:77], v[44:45]
	v_pk_add_f32 v[24:25], v[24:25], v[46:47]
	v_mov_b32_e32 v100, v99
	v_pk_add_f32 v[24:25], v[24:25], v[100:101]
	v_mov_b32_e32 v46, v28
	v_mov_b32_e32 v47, v44
	v_pk_add_f32 v[24:25], v[24:25], v[46:47]
	v_mov_b32_e32 v44, v29
	v_pk_add_f32 v[24:25], v[24:25], v[44:45]
	v_lshlrev_b32_e32 v28, 16, v123
	v_lshlrev_b32_e32 v29, 16, v190
	v_mov_b32_e32 v44, v74
	v_mov_b32_e32 v45, v78
	v_pk_mul_f32 v[28:29], v[44:45], v[28:29]
	v_and_b32_e32 v45, 0xffff0000, v190
	v_and_b32_e32 v44, 0xffff0000, v123
	v_mov_b32_e32 v78, v75
	v_mov_b32_e32 v46, v94
	v_mov_b32_e32 v47, v96
	v_pk_mul_f32 v[44:45], v[78:79], v[44:45]
	v_pk_add_f32 v[26:27], v[26:27], v[46:47]
	v_mov_b32_e32 v96, v95
	v_pk_add_f32 v[26:27], v[26:27], v[96:97]
	v_mov_b32_e32 v46, v28
	v_mov_b32_e32 v47, v44
	v_pk_add_f32 v[26:27], v[26:27], v[46:47]
	v_mov_b32_e32 v44, v29
	v_pk_add_f32 v[26:27], v[26:27], v[44:45]
	ds_read_b128 v[44:47], v124 offset:39360
	ds_read_b128 v[48:51], v124 offset:39376
	v_lshlrev_b32_e32 v28, 16, v120
	v_and_b32_e32 v29, 0xffff0000, v120
	v_pk_fma_f32 v[16:17], v[20:21], v[28:29], v[16:17]
	v_lshlrev_b32_e32 v20, 16, v0
	v_and_b32_e32 v21, 0xffff0000, v0
	v_pk_fma_f32 v[16:17], v[40:41], v[20:21], v[16:17]
	v_lshlrev_b32_e32 v20, 16, v121
	v_and_b32_e32 v21, 0xffff0000, v121
	v_pk_fma_f32 v[16:17], v[56:57], v[20:21], v[16:17]
	v_lshlrev_b32_e32 v20, 16, v122
	v_and_b32_e32 v21, 0xffff0000, v122
	s_waitcnt lgkmcnt(0)
	v_pk_fma_f32 v[16:17], v[44:45], v[20:21], v[16:17]
	v_lshlrev_b32_e32 v20, 16, v117
	v_and_b32_e32 v21, 0xffff0000, v117
	v_pk_fma_f32 v[18:19], v[22:23], v[20:21], v[18:19]
	v_lshlrev_b32_e32 v0, 16, v1
	v_and_b32_e32 v1, 0xffff0000, v1
	v_pk_fma_f32 v[0:1], v[42:43], v[0:1], v[18:19]
	v_lshlrev_b32_e32 v18, 16, v118
	v_and_b32_e32 v19, 0xffff0000, v118
	v_pk_fma_f32 v[0:1], v[58:59], v[18:19], v[0:1]
	v_lshlrev_b32_e32 v18, 16, v119
	v_and_b32_e32 v19, 0xffff0000, v119
	v_pk_fma_f32 v[18:19], v[46:47], v[18:19], v[0:1]
	v_lshlrev_b32_e32 v0, 16, v115
	v_lshlrev_b32_e32 v1, 16, v116
	v_mov_b32_e32 v20, v30
	v_mov_b32_e32 v21, v48
	v_pk_mul_f32 v[0:1], v[20:21], v[0:1]
	v_and_b32_e32 v21, 0xffff0000, v116
	v_and_b32_e32 v20, 0xffff0000, v115
	v_mov_b32_e32 v48, v31
	v_mov_b32_e32 v22, v90
	v_mov_b32_e32 v23, v92
	v_pk_mul_f32 v[20:21], v[48:49], v[20:21]
	v_pk_add_f32 v[8:9], v[8:9], v[22:23]
	v_mov_b32_e32 v92, v91
	v_pk_add_f32 v[8:9], v[8:9], v[92:93]
	v_mov_b32_e32 v22, v0
	v_mov_b32_e32 v23, v20
	v_pk_add_f32 v[8:9], v[8:9], v[22:23]
	v_mov_b32_e32 v20, v1
	v_pk_add_f32 v[8:9], v[8:9], v[20:21]
	v_lshlrev_b32_e32 v0, 16, v113
	v_lshlrev_b32_e32 v1, 16, v114
	v_mov_b32_e32 v20, v32
	v_mov_b32_e32 v21, v50
	v_mov_b32_e32 v22, v6
	v_mov_b32_e32 v23, v34
	v_pk_mul_f32 v[0:1], v[20:21], v[0:1]
	v_and_b32_e32 v21, 0xffff0000, v114
	v_and_b32_e32 v20, 0xffff0000, v113
	v_mov_b32_e32 v50, v33
	v_pk_add_f32 v[10:11], v[10:11], v[22:23]
	v_mov_b32_e32 v34, v7
	v_pk_mul_f32 v[20:21], v[50:51], v[20:21]
	v_pk_add_f32 v[6:7], v[10:11], v[34:35]
	v_mov_b32_e32 v10, v0
	v_mov_b32_e32 v0, s44
	v_mov_b32_e32 v11, v20
	v_mad_u32_u24 v28, v110, s55, v0
	v_pk_add_f32 v[6:7], v[6:7], v[10:11]
	v_mov_b32_e32 v20, v1
	v_add_u32_e32 v0, v28, v88
	v_pk_add_f32 v[10:11], v[6:7], v[20:21]
	v_cvt_pk_bf16_f32 v32, v36, v37
	v_cvt_pk_bf16_f32 v33, v38, v39
	v_cvt_pk_bf16_f32 v34, v52, v53
	v_cvt_pk_bf16_f32 v35, v54, v55
	ds_write_b128 v0, v[36:39] offset:40960
	ds_write_b128 v0, v[52:55] offset:40976
	v_cvt_pk_bf16_f32 v36, v64, v65
	v_cvt_pk_bf16_f32 v37, v66, v67
	v_cvt_pk_bf16_f32 v38, v12, v13
	v_cvt_pk_bf16_f32 v39, v14, v15
	ds_write_b128 v0, v[64:67] offset:41024
	ds_write_b128 v0, v[12:15] offset:41040
	v_cvt_pk_bf16_f32 v40, v2, v3
	v_cvt_pk_bf16_f32 v41, v4, v5
	v_cvt_pk_bf16_f32 v42, v24, v25
	v_cvt_pk_bf16_f32 v43, v26, v27
	ds_write_b128 v0, v[2:5] offset:41088
	ds_write_b128 v0, v[24:27] offset:41104
	v_cvt_pk_bf16_f32 v44, v16, v17
	v_cvt_pk_bf16_f32 v45, v18, v19
	v_cvt_pk_bf16_f32 v46, v8, v9
	v_cvt_pk_bf16_f32 v47, v10, v11
	ds_write_b128 v0, v[16:19] offset:41152
	ds_write_b128 v0, v[8:11] offset:41168
	s_waitcnt lgkmcnt(0)
	v_lshl_add_u32 v84, v112, 4, 0
	v_mad_u32_u24 v70, v110, s69, v84
	ds_read_b128 v[0:3], v70
	ds_read_b128 v[16:19], v70 offset:32
	s_waitcnt lgkmcnt(0)
	v_mfma_f32_32x32x16_bf16 v[0:15], v[32:35], v[0:3], 0
	ds_read_b128 v[20:23], v70 offset:96
	v_mul_i32_i24_e32 v24, 0xfffffef4, v110
	v_mul_lo_u32 v25, v112, s61
	v_add3_u32 v74, v28, v24, v25
	v_add_u32_e32 v24, 0xa800, v74
	v_add_u32_e32 v48, 0xb000, v74
	v_add_u32_e32 v54, 0xb800, v74
	v_mfma_f32_32x32x16_bf16 v[0:15], v[36:39], v[16:19], v[0:15]
	ds_read_b128 v[16:19], v70 offset:64
	v_add_u32_e32 v71, 0xba00, v74
	s_mul_hi_i32 s8, s4, 0x7e07e07f
	s_lshr_b32 s9, s8, 31
	s_ashr_i32 s8, s8, 5
	s_add_i32 s8, s8, s9
	s_mul_i32 s9, s8, 0x41
	s_waitcnt lgkmcnt(0)
; #define LAS __attribute__((address_space(3)))
; template <int PASS>
; __device__ __forceinline__ void lru_item(Frame& F, const LAS bf16* lw, const LAS float* prm, const LAS float* cwl, LAS float* xs, LAS unsigned char* pf, int head, int item, int nitem) {
;     ...
;     float xd[2][16];
; #pragma unroll
;     for (int ct = 0; ct < 2; ++ct)
; #pragma unroll
;         for (int rg = 0; rg < 16; ++rg) xd[ct][rg] = xs[((rg & 3) + 8 * (rg >> 2) + 4 * hh) * 68 + t + 32 * ct];
;     float ysum[2][16];
; #pragma unroll
;     for (int d = 0; d < 2; ++d) {
; #pragma unroll
;         for (int ct = 0; ct < 2; ++ct) {
;             f32x16 acc[2];
; #pragma unroll
;             for (int gt = 0; gt < 2; ++gt) {
;                 f32x16 a; for (int i = 0; i < 16; ++i) a[i] = 0.f;
;                 const LAS bf16* wb = lw + ((d * 2 + gt) * 64 + t + 32 * ct) * LRU_WROW + 8 * hh;
; #pragma unroll
;                 for (int ks = 0; ks < 4; ++ks) a = __builtin_amdgcn_mfma_f32_32x32x16_bf16(af[ks], *(const LAS bf16x8*)(wb + 16 * ks), a, 0, 0, 0);
;                 acc[gt] = a;
;             }
;             const int chl = t + 32 * ct, ch = head * 64 + chl;
;             float av[16], bv[16];
;             {
;                 const float br = prm[(d * 3 + 0) * 64 + chl], bi = prm[(d * 3 + 1) * 64 + chl], c8 = prm[(d * 3 + 2) * 64 + chl];
; #pragma unroll
;                 for (int rg = 0; rg < 16; ++rg) {
;                     const float rr = __builtin_amdgcn_rcpf(1.f + __builtin_amdgcn_exp2f(acc[0][rg] + br)), ei = 1.f + __builtin_amdgcn_exp2f(acc[1][rg] + bi);
;                     const float a = __builtin_amdgcn_exp2f(c8 * rr), om = fmaxf(fmaf(-a, a, 1.f), 1e-30f);
;                     av[rg] = a; bv[rg] = (om * __builtin_amdgcn_rsqf(om * ei * ei)) * xd[ct][rg];
;                 }
;             }
	v_mfma_f32_32x32x16_bf16 v[0:15], v[40:43], v[16:19], v[0:15]
	v_add_u32_e32 v16, 0xa000, v74
	ds_read2_b32 v[58:59], v16 offset1:32
	ds_read2_b32 v[64:65], v16 offset0:68 offset1:100
	ds_read2_b32 v[68:69], v16 offset0:136 offset1:168
	ds_read2_b32 v[72:73], v16 offset0:204 offset1:236
	ds_read2_b32 v[50:51], v24 offset0:32 offset1:64
	ds_read2_b32 v[60:61], v24 offset0:100 offset1:132
	ds_read_b128 v[16:19], v70 offset:9216
	ds_read2_b32 v[66:67], v24 offset0:168 offset1:200
	s_sub_i32 s4, s4, s9
	s_lshl_b32 s9, s4, 3
	s_add_i32 s9, s9, 8
	s_cmp_lt_i32 s4, 64
	v_mfma_f32_32x32x16_bf16 v[0:15], v[44:47], v[20:23], v[0:15]
	v_add_u32_e32 v20, 0xaa00, v74
	ds_read2_b32 v[78:79], v20 offset0:108 offset1:140
	ds_read_b128 v[80:83], v70 offset:9248
	ds_read2_b32 v[52:53], v48 offset0:64 offset1:96
	ds_read2_b32 v[56:57], v48 offset0:132 offset1:164
	ds_read2_b32 v[62:63], v48 offset0:200 offset1:232
	v_add_u32_e32 v48, 0xb400, v74
	ds_read2_b32 v[76:77], v48 offset0:12 offset1:44
	ds_read2_b32 v[48:49], v54 offset0:96 offset1:128
	ds_read2_b32 v[54:55], v54 offset0:164 offset1:196
	ds_read_b128 v[90:93], v70 offset:9280
	ds_read_b128 v[94:97], v70 offset:9312
	s_waitcnt lgkmcnt(0)
	v_mfma_f32_32x32x16_bf16 v[16:31], v[32:35], v[16:19], 0
	v_add_u32_e32 v74, 0xbc00, v74
	ds_read2_b32 v[74:75], v74 offset0:44 offset1:76
	s_cselect_b32 s4, s9, 0
	s_or_b32 s4, s4, s17
	s_mulk_i32 s8, 0x410
	s_add_i32 s8, s4, s8
	s_ashr_i32 s9, s8, 31
	v_mfma_f32_32x32x16_bf16 v[16:31], v[36:39], v[80:83], v[16:31]
	v_lshl_add_u32 v83, v110, 2, 0
	ds_read2st64_b32 v[80:81], v83 offset0:144 offset1:145
	ds_read_b32 v85, v83 offset:37376
	ds_read2_b32 v[70:71], v71 offset0:104 offset1:136
	v_lshlrev_b32_e32 v82, 2, v111
	v_xor_b32_e32 v82, 0x80, v82
	s_waitcnt lgkmcnt(0)
	v_add_f32_e32 v4, v4, v80
	v_mfma_f32_32x32x16_bf16 v[16:31], v[40:43], v[90:93], v[16:31]
	v_exp_f32_e32 v4, v4
	v_add_f32_e32 v5, v5, v80
	v_exp_f32_e32 v5, v5
	v_add_f32_e32 v6, v6, v80
	v_add_f32_e32 v4, 1.0, v4
	v_rcp_f32_e32 v4, v4
	v_exp_f32_e32 v6, v6
	v_mfma_f32_32x32x16_bf16 v[16:31], v[44:47], v[94:97], v[16:31]
	v_add_f32_e32 v5, 1.0, v5
	v_mul_f32_e32 v4, v85, v4
	v_exp_f32_e32 v4, v4
	v_rcp_f32_e32 v5, v5
	v_add_f32_e32 v6, 1.0, v6
	v_rcp_f32_e32 v6, v6
	v_fma_f32 v86, -v4, v4, 1.0
	s_nop 4
	v_add_f32_e32 v20, v20, v81
	v_exp_f32_e32 v20, v20
	v_max_f32_e32 v86, 0xda24260, v86
	v_add_f32_e32 v7, v7, v80
	v_mul_f32_e32 v5, v85, v5
	v_add_f32_e32 v20, 1.0, v20
	v_mul_f32_e32 v87, v20, v86
	v_mul_f32_e32 v20, v20, v87
	v_exp_f32_e32 v7, v7
	v_rsq_f32_e32 v20, v20
	v_add_f32_e32 v21, v21, v81
	v_exp_f32_e32 v5, v5
	v_exp_f32_e32 v21, v21
	v_add_f32_e32 v8, v8, v80
	v_mul_f32_e32 v6, v85, v6
	v_exp_f32_e32 v8, v8
	v_add_f32_e32 v22, v22, v81
	v_exp_f32_e32 v6, v6
	v_add_f32_e32 v7, 1.0, v7
	v_mul_f32_e32 v20, v86, v20
	v_fma_f32 v86, -v5, v5, 1.0
	v_exp_f32_e32 v22, v22
	v_rcp_f32_e32 v7, v7
	v_add_f32_e32 v21, 1.0, v21
	v_max_f32_e32 v86, 0xda24260, v86
	v_mul_f32_e32 v87, v21, v86
	v_add_f32_e32 v8, 1.0, v8
	v_mul_f32_e32 v21, v21, v87
	v_fma_f32 v87, -v6, v6, 1.0
	v_rcp_f32_e32 v8, v8
	v_add_f32_e32 v9, v9, v80
	v_add_f32_e32 v22, 1.0, v22
	v_max_f32_e32 v87, 0xda24260, v87
	v_mul_f32_e32 v7, v85, v7
	v_exp_f32_e32 v9, v9
	v_rsq_f32_e32 v21, v21
	v_mul_f32_e32 v88, v22, v87
	v_add_f32_e32 v23, v23, v81
	v_exp_f32_e32 v7, v7
	v_mul_f32_e32 v22, v22, v88
	v_exp_f32_e32 v23, v23
	v_rsq_f32_e32 v22, v22
	v_mul_f32_e32 v8, v85, v8
	v_add_f32_e32 v24, v24, v81
	v_exp_f32_e32 v8, v8
	v_add_f32_e32 v9, 1.0, v9
	v_mul_f32_e32 v21, v86, v21
	v_fma_f32 v86, -v7, v7, 1.0
	v_exp_f32_e32 v24, v24
	v_rcp_f32_e32 v9, v9
	v_add_f32_e32 v23, 1.0, v23
	v_max_f32_e32 v86, 0xda24260, v86
	v_mul_f32_e32 v22, v87, v22
	v_mul_f32_e32 v87, v23, v86
	v_add_f32_e32 v10, v10, v80
	v_mul_f32_e32 v23, v23, v87
	v_fma_f32 v87, -v8, v8, 1.0
	v_exp_f32_e32 v10, v10
	v_add_f32_e32 v24, 1.0, v24
	v_max_f32_e32 v87, 0xda24260, v87
	v_mul_f32_e32 v9, v85, v9
	v_rsq_f32_e32 v23, v23
	v_mul_f32_e32 v88, v24, v87
	v_add_f32_e32 v25, v25, v81
	v_exp_f32_e32 v9, v9
	v_add_f32_e32 v11, v11, v80
	v_mul_f32_e32 v24, v24, v88
	v_exp_f32_e32 v25, v25
	v_exp_f32_e32 v11, v11
	v_rsq_f32_e32 v24, v24
	v_add_f32_e32 v10, 1.0, v10
	v_rcp_f32_e32 v10, v10
	v_mul_f32_e32 v23, v86, v23
	v_fma_f32 v86, -v9, v9, 1.0
	v_add_f32_e32 v25, 1.0, v25
	v_max_f32_e32 v86, 0xda24260, v86
	v_add_f32_e32 v11, 1.0, v11
	v_mul_f32_e32 v24, v87, v24
	v_mul_f32_e32 v87, v25, v86
	v_rcp_f32_e32 v11, v11
	v_add_f32_e32 v12, v12, v80
	v_mul_f32_e32 v25, v25, v87
	v_mul_f32_e32 v10, v85, v10
	v_exp_f32_e32 v12, v12
	v_rsq_f32_e32 v25, v25
	v_add_f32_e32 v26, v26, v81
	v_exp_f32_e32 v10, v10
	v_exp_f32_e32 v26, v26
	v_mul_f32_e32 v11, v85, v11
	v_add_f32_e32 v27, v27, v81
	v_exp_f32_e32 v11, v11
	v_add_f32_e32 v12, 1.0, v12
	v_mul_f32_e32 v25, v86, v25
	v_fma_f32 v86, -v10, v10, 1.0
	v_exp_f32_e32 v27, v27
	v_rcp_f32_e32 v12, v12
	v_add_f32_e32 v26, 1.0, v26
	v_max_f32_e32 v86, 0xda24260, v86
	v_mul_f32_e32 v87, v26, v86
	v_add_f32_e32 v13, v13, v80
	v_mul_f32_e32 v26, v26, v87
	v_fma_f32 v87, -v11, v11, 1.0
	v_exp_f32_e32 v13, v13
	v_add_f32_e32 v27, 1.0, v27
	v_max_f32_e32 v87, 0xda24260, v87
	v_mul_f32_e32 v12, v85, v12
	v_rsq_f32_e32 v26, v26
	v_mul_f32_e32 v88, v27, v87
	v_add_f32_e32 v28, v28, v81
	v_exp_f32_e32 v12, v12
	v_add_f32_e32 v14, v14, v80
	v_mul_f32_e32 v27, v27, v88
	v_exp_f32_e32 v28, v28
	v_exp_f32_e32 v14, v14
	v_rsq_f32_e32 v27, v27
	v_add_f32_e32 v13, 1.0, v13
	v_rcp_f32_e32 v13, v13
	v_add_f32_e32 v15, v15, v80
	v_mul_f32_e32 v26, v86, v26
	v_fma_f32 v86, -v12, v12, 1.0
	v_exp_f32_e32 v15, v15
	v_add_f32_e32 v28, 1.0, v28
; __device__ __forceinline__ float shx(float v, int o, int lane) { return __int_as_float(__builtin_amdgcn_ds_bpermute((lane ^ o) << 2, __float_as_int(v))); }
; __device__ __forceinline__ int shx(int v, int o, int lane) { return __builtin_amdgcn_ds_bpermute((lane ^ o) << 2, v); }
; template <int PASS>
; __device__ __forceinline__ void lru_item(Frame& F, const LAS bf16* lw, const LAS float* prm, const LAS float* cwl, LAS float* xs, LAS unsigned char* pf, int head, int item, int nitem) {
;     ...
;             float hl[16], cp[16], sA[4], sB[4];
; #pragma unroll
;             for (int q4 = 0; q4 < 4; ++q4) {
;                 if (d == 0) {
;                     hl[4 * q4] = bv[4 * q4]; cp[4 * q4] = av[4 * q4];
; #pragma unroll
;                     for (int i = 1; i < 4; ++i) { hl[4 * q4 + i] = av[4 * q4 + i] * hl[4 * q4 + i - 1] + bv[4 * q4 + i]; cp[4 * q4 + i] = av[4 * q4 + i] * cp[4 * q4 + i - 1]; }
;                     sA[q4] = cp[4 * q4 + 3]; sB[q4] = hl[4 * q4 + 3];
;                 } else {
;                     hl[4 * q4 + 3] = bv[4 * q4 + 3]; cp[4 * q4 + 3] = av[4 * q4 + 3];
; #pragma unroll
;                     for (int i = 2; i >= 0; --i) { hl[4 * q4 + i] = av[4 * q4 + i] * hl[4 * q4 + i + 1] + bv[4 * q4 + i]; cp[4 * q4 + i] = av[4 * q4 + i] * cp[4 * q4 + i + 1]; }
;                     sA[q4] = cp[4 * q4]; sB[q4] = hl[4 * q4];
;                 }
;             }
;             float Ae[4], Be[4], Ao[4], Bo[4];
; #pragma unroll
;             for (int q4 = 0; q4 < 4; ++q4) {
;                 const float oA = shx(sA[q4], 32, lane), oB = shx(sB[q4], 32, lane);
;                 Ae[q4] = hh ? oA : sA[q4]; Be[q4] = hh ? oB : sB[q4]; Ao[q4] = hh ? sA[q4] : oA; Bo[q4] = hh ? sB[q4] : oB;
;             }
;             if (PASS == 1) {
;                 float c = 0.f, P = 1.f;
;                 if (d == 0) {
; #pragma unroll
;                     for (int q4 = 0; q4 < 4; ++q4) { c = Ae[q4] * c + Be[q4]; c = Ao[q4] * c + Bo[q4]; P *= Ae[q4] * Ao[q4]; } }
;                 else {
; #pragma unroll
;     ...
;                 if (hh == 0) { float* o = (float*)(F.ws + WS_PL) + ((size_t)((b * 2 + d) * NQ + q) * 1024 + ch) * 2; o[0] = P; o[1] = c; }
	v_max_f32_e32 v86, 0xda24260, v86
	v_add_f32_e32 v14, 1.0, v14
	v_mul_f32_e32 v27, v87, v27
	v_mul_f32_e32 v87, v28, v86
	v_rcp_f32_e32 v14, v14
	v_add_f32_e32 v3, v3, v80
	v_mul_f32_e32 v28, v28, v87
	v_mul_f32_e32 v13, v85, v13
	v_exp_f32_e32 v3, v3
	v_rsq_f32_e32 v28, v28
	v_add_f32_e32 v29, v29, v81
	v_exp_f32_e32 v13, v13
	v_add_f32_e32 v15, 1.0, v15
	v_exp_f32_e32 v29, v29
	v_rcp_f32_e32 v15, v15
	v_add_f32_e32 v2, v2, v80
	v_mul_f32_e32 v14, v85, v14
	v_exp_f32_e32 v2, v2
	v_add_f32_e32 v0, v0, v80
	v_add_f32_e32 v30, v30, v81
	v_exp_f32_e32 v14, v14
	v_add_f32_e32 v3, 1.0, v3
	v_exp_f32_e32 v0, v0
	v_mul_f32_e32 v28, v86, v28
	v_fma_f32 v86, -v13, v13, 1.0
	v_exp_f32_e32 v30, v30
	v_rcp_f32_e32 v3, v3
	v_add_f32_e32 v1, v1, v80
	v_add_f32_e32 v29, 1.0, v29
	v_max_f32_e32 v86, 0xda24260, v86
	v_mul_f32_e32 v15, v85, v15
	v_exp_f32_e32 v1, v1
	v_mul_f32_e32 v87, v29, v86
	v_add_f32_e32 v31, v31, v81
	v_exp_f32_e32 v15, v15
	v_add_f32_e32 v2, 1.0, v2
	v_mul_f32_e32 v29, v29, v87
	v_fma_f32 v87, -v14, v14, 1.0
	v_exp_f32_e32 v31, v31
	v_rcp_f32_e32 v2, v2
	v_add_f32_e32 v0, 1.0, v0
	v_add_f32_e32 v30, 1.0, v30
	v_max_f32_e32 v87, 0xda24260, v87
	v_mul_f32_e32 v3, v85, v3
	v_rcp_f32_e32 v0, v0
	v_rsq_f32_e32 v29, v29
	v_mul_f32_e32 v88, v30, v87
	v_exp_f32_e32 v3, v3
	v_add_f32_e32 v19, v19, v81
	v_add_f32_e32 v1, 1.0, v1
	v_mul_f32_e32 v30, v30, v88
	v_fma_f32 v88, -v15, v15, 1.0
	v_exp_f32_e32 v19, v19
	v_rcp_f32_e32 v1, v1
	v_rsq_f32_e32 v30, v30
	v_add_f32_e32 v31, 1.0, v31
	v_max_f32_e32 v88, 0xda24260, v88
	v_mul_f32_e32 v2, v85, v2
	v_mul_f32_e32 v90, v31, v88
	v_exp_f32_e32 v2, v2
	v_add_f32_e32 v18, v18, v81
	v_mul_f32_e32 v0, v85, v0
	v_mul_f32_e32 v31, v31, v90
	v_mul_f32_e32 v29, v86, v29
	v_fma_f32 v86, -v3, v3, 1.0
	v_exp_f32_e32 v18, v18
	v_exp_f32_e32 v0, v0
	v_add_f32_e32 v16, v16, v81
	v_rsq_f32_e32 v31, v31
	v_max_f32_e32 v86, 0xda24260, v86
	v_add_f32_e32 v19, 1.0, v19
	v_mul_f32_e32 v1, v85, v1
	v_exp_f32_e32 v16, v16
	v_mul_f32_e32 v30, v87, v30
	v_mul_f32_e32 v87, v19, v86
	v_exp_f32_e32 v1, v1
	v_add_f32_e32 v17, v17, v81
	v_mul_f32_e32 v19, v19, v87
	v_fma_f32 v87, -v2, v2, 1.0
	v_exp_f32_e32 v17, v17
	v_max_f32_e32 v87, 0xda24260, v87
	v_add_f32_e32 v18, 1.0, v18
	v_fma_f32 v81, -v0, v0, 1.0
	v_mul_f32_e32 v31, v88, v31
	v_mul_f32_e32 v88, v18, v87
	v_max_f32_e32 v81, 0xda24260, v81
	v_add_f32_e32 v16, 1.0, v16
	v_mul_f32_e32 v18, v18, v88
	v_fma_f32 v88, -v1, v1, 1.0
	v_mul_f32_e32 v85, v16, v81
	v_max_f32_e32 v80, 0xda24260, v88
	v_add_f32_e32 v17, 1.0, v17
	v_mul_f32_e32 v16, v16, v85
	v_mul_f32_e32 v88, v17, v80
	v_rsq_f32_e32 v16, v16
	v_mul_f32_e32 v17, v17, v88
	v_rsq_f32_e32 v17, v17
	v_rsq_f32_e32 v18, v18
	v_mul_f32_e32 v16, v81, v16
	v_mul_f32_e32 v16, v58, v16
	v_mul_f32_e32 v17, v80, v17
	v_mul_f32_e32 v16, v1, v16
	v_fmac_f32_e32 v16, v64, v17
	v_mul_f32_e32 v18, v87, v18
	v_mul_f32_e32 v0, v0, v1
	v_mul_f32_e32 v1, v2, v16
	v_mul_f32_e32 v20, v50, v20
	v_fmac_f32_e32 v1, v68, v18
	v_mul_f32_e32 v0, v2, v0
	v_mul_f32_e32 v2, v3, v1
	v_mul_f32_e32 v3, v3, v0
	v_mul_f32_e32 v0, v5, v20
	v_fmac_f32_e32 v0, v60, v21
	v_mul_f32_e32 v0, v6, v0
	v_mul_f32_e32 v24, v52, v24
	v_fmac_f32_e32 v0, v66, v22
	v_mul_f32_e32 v1, v4, v5
	v_mul_f32_e32 v4, v7, v0
	v_mul_f32_e32 v0, v9, v24
	v_fmac_f32_e32 v0, v56, v25
	v_mul_f32_e32 v0, v10, v0
	v_mul_f32_e32 v28, v48, v28
	v_fmac_f32_e32 v0, v62, v26
	v_rsq_f32_e32 v19, v19
	v_mul_f32_e32 v1, v6, v1
	v_mul_f32_e32 v6, v11, v0
	v_mul_f32_e32 v0, v13, v28
	v_mul_f32_e32 v5, v7, v1
	v_mul_f32_e32 v1, v8, v9
	v_fmac_f32_e32 v0, v54, v29
	v_mul_f32_e32 v1, v10, v1
	v_mul_f32_e32 v0, v14, v0
	v_mul_f32_e32 v7, v11, v1
	v_mul_f32_e32 v1, v12, v13
	v_fmac_f32_e32 v0, v70, v30
	v_mul_f32_e32 v19, v86, v19
	v_mul_f32_e32 v1, v14, v1
	v_mul_f32_e32 v8, v15, v0
	v_fmac_f32_e32 v2, v72, v19
	v_fmac_f32_e32 v4, v78, v23
	v_fmac_f32_e32 v6, v76, v27
	v_fmac_f32_e32 v8, v74, v31
	v_mul_f32_e32 v9, v15, v1
	s_nop 1
	v_permlane32_swap_b32 v3, v16
	v_permlane32_swap_b32 v2, v15
	v_permlane32_swap_b32 v5, v14
	v_permlane32_swap_b32 v4, v13
	v_permlane32_swap_b32 v7, v12
	v_permlane32_swap_b32 v6, v11
	v_permlane32_swap_b32 v9, v10
	v_permlane32_swap_b32 v8, v1
	v_cmp_gt_u32_e32 vcc, 32, v111
	s_lshl_b64 s[10:11], s[8:9], 11
	v_lshl_or_b32 v88, v111, 1, s16
	s_and_saveexec_b64 s[12:13], vcc
	s_cbranch_execz .LBB0_704
	v_fmac_f32_e32 v2, 0, v3
	s_waitcnt lgkmcnt(0)
	v_fmac_f32_e32 v15, v2, v16
	v_fmac_f32_e32 v4, v5, v15
	v_fmac_f32_e32 v13, v4, v14
	v_mul_f32_e32 v0, v3, v16
	v_mul_f32_e32 v17, v5, v14
	v_fmac_f32_e32 v6, v7, v13
	s_lshl_b64 s[62:63], s[10:11], 2
	v_mul_f32_e32 v0, v0, v17
	v_mul_f32_e32 v17, v7, v12
	v_fmac_f32_e32 v11, v6, v12
	s_add_u32 s62, s19, s62
	v_mul_f32_e32 v0, v17, v0
	v_mul_f32_e32 v17, v9, v10
	v_fmac_f32_e32 v8, v9, v11
	s_addc_u32 s63, s30, s63
	v_mul_f32_e32 v0, v17, v0
	v_fmac_f32_e32 v1, v8, v10
	v_lshl_add_u64 v[2:3], v[88:89], 2, s[62:63]
	global_store_dwordx2 v[2:3], v[0:1], off
; #define LAS __attribute__((address_space(3)))
; template <int PASS>
; __device__ __forceinline__ void lru_item(Frame& F, const LAS bf16* lw, const LAS float* prm, const LAS float* cwl, LAS float* xs, LAS unsigned char* pf, int head, int item, int nitem) {
;     ...
;     for (int d = 0; d < 2; ++d) {
; #pragma unroll
;         for (int ct = 0; ct < 2; ++ct) {
;             f32x16 acc[2];
; #pragma unroll
;             for (int gt = 0; gt < 2; ++gt) {
;                 f32x16 a; for (int i = 0; i < 16; ++i) a[i] = 0.f;
;                 const LAS bf16* wb = lw + ((d * 2 + gt) * 64 + t + 32 * ct) * LRU_WROW + 8 * hh;
; #pragma unroll
;                 for (int ks = 0; ks < 4; ++ks) a = __builtin_amdgcn_mfma_f32_32x32x16_bf16(af[ks], *(const LAS bf16x8*)(wb + 16 * ks), a, 0, 0, 0);
;                 acc[gt] = a;
;             }
;             const int chl = t + 32 * ct, ch = head * 64 + chl;
;             float av[16], bv[16];
;             {
;                 const float br = prm[(d * 3 + 0) * 64 + chl], bi = prm[(d * 3 + 1) * 64 + chl], c8 = prm[(d * 3 + 2) * 64 + chl];
; #pragma unroll
;                 for (int rg = 0; rg < 16; ++rg) {
;                     const float rr = __builtin_amdgcn_rcpf(1.f + __builtin_amdgcn_exp2f(acc[0][rg] + br)), ei = 1.f + __builtin_amdgcn_exp2f(acc[1][rg] + bi);
;                     const float a = __builtin_amdgcn_exp2f(c8 * rr), om = fmaxf(fmaf(-a, a, 1.f), 1e-30f);
;                     av[rg] = a; bv[rg] = (om * __builtin_amdgcn_rsqf(om * ei * ei)) * xd[ct][rg];
;                 }
;             }
.LBB0_704:
	s_or_b64 exec, exec, s[12:13]
	v_mul_u32_u24_e32 v0, 0x90, v110
	v_add_u32_e32 v85, v84, v0
	s_waitcnt lgkmcnt(0)
	ds_read_b128 v[0:3], v85 offset:4608
	ds_read_b32 v84, v83 offset:37504
	v_add_u32_e32 v86, 0x80, v83
	s_waitcnt lgkmcnt(0)
	v_mfma_f32_32x32x16_bf16 v[16:31], v[32:35], v[0:3], 0
	ds_read_b128 v[0:3], v85 offset:4640
	ds_read_b128 v[4:7], v85 offset:4672
	s_waitcnt lgkmcnt(0)
	v_mfma_f32_32x32x16_bf16 v[16:31], v[36:39], v[0:3], v[16:31]
	v_mfma_f32_32x32x16_bf16 v[16:31], v[40:43], v[4:7], v[16:31]
	ds_read_b128 v[0:3], v85 offset:4704
	ds_read_b128 v[4:7], v85 offset:13824
	ds_read_b128 v[90:93], v85 offset:13856
	ds_read_b128 v[94:97], v85 offset:13888
	ds_read2st64_b32 v[80:81], v86 offset0:144 offset1:145
	s_waitcnt lgkmcnt(0)
	v_mfma_f32_32x32x16_bf16 v[16:31], v[44:47], v[0:3], v[16:31]
	v_mfma_f32_32x32x16_bf16 v[0:15], v[32:35], v[4:7], 0
	s_nop 10
	v_add_f32_e32 v20, v20, v80
	v_exp_f32_e32 v20, v20
	v_add_f32_e32 v21, v21, v80
	v_exp_f32_e32 v21, v21
	v_add_f32_e32 v22, v22, v80
	v_add_f32_e32 v20, 1.0, v20
	v_rcp_f32_e32 v20, v20
	v_mfma_f32_32x32x16_bf16 v[0:15], v[36:39], v[90:93], v[0:15]
	ds_read_b128 v[90:93], v85 offset:13920
	v_exp_f32_e32 v22, v22
	v_mul_f32_e32 v20, v84, v20
	v_exp_f32_e32 v20, v20
	v_add_f32_e32 v21, 1.0, v21
	v_rcp_f32_e32 v21, v21
	v_add_f32_e32 v22, 1.0, v22
	v_mfma_f32_32x32x16_bf16 v[0:15], v[40:43], v[94:97], v[0:15]
	v_fma_f32 v87, -v20, v20, 1.0
	v_max_f32_e32 v87, 0xda24260, v87
	v_rcp_f32_e32 v22, v22
	v_add_f32_e32 v23, v23, v80
	v_mul_f32_e32 v21, v84, v21
	v_exp_f32_e32 v23, v23
	v_exp_f32_e32 v21, v21
	s_waitcnt lgkmcnt(0)
	v_mfma_f32_32x32x16_bf16 v[0:15], v[44:47], v[90:93], v[0:15]
	v_add_f32_e32 v24, v24, v80
	v_mul_f32_e32 v22, v84, v22
	v_exp_f32_e32 v24, v24
	v_exp_f32_e32 v22, v22
	v_add_f32_e32 v23, 1.0, v23
	v_rcp_f32_e32 v23, v23
	v_add_f32_e32 v24, 1.0, v24
	s_nop 4
	v_add_f32_e32 v4, v4, v81
	v_exp_f32_e32 v4, v4
	v_add_f32_e32 v5, v5, v81
	v_exp_f32_e32 v5, v5
	v_add_f32_e32 v6, v6, v81
	v_add_f32_e32 v4, 1.0, v4
	v_mul_f32_e32 v90, v4, v87
	v_mul_f32_e32 v4, v4, v90
	v_rsq_f32_e32 v4, v4
	v_exp_f32_e32 v6, v6
	v_add_f32_e32 v5, 1.0, v5
	v_rcp_f32_e32 v24, v24
	v_mul_f32_e32 v4, v87, v4
	v_fma_f32 v87, -v21, v21, 1.0
	v_max_f32_e32 v87, 0xda24260, v87
	v_mul_f32_e32 v90, v5, v87
	v_mul_f32_e32 v5, v5, v90
	v_fma_f32 v90, -v22, v22, 1.0
	v_add_f32_e32 v25, v25, v80
	v_add_f32_e32 v6, 1.0, v6
	v_max_f32_e32 v90, 0xda24260, v90
	v_mul_f32_e32 v23, v84, v23
	v_exp_f32_e32 v25, v25
	v_rsq_f32_e32 v5, v5
	v_mul_f32_e32 v91, v6, v90
	v_add_f32_e32 v7, v7, v81
	v_exp_f32_e32 v23, v23
	v_mul_f32_e32 v6, v6, v91
	v_exp_f32_e32 v7, v7
	v_rsq_f32_e32 v6, v6
	v_mul_f32_e32 v24, v84, v24
	v_add_f32_e32 v8, v8, v81
	v_exp_f32_e32 v24, v24
	v_add_f32_e32 v25, 1.0, v25
	v_mul_f32_e32 v5, v87, v5
	v_fma_f32 v87, -v23, v23, 1.0
	v_exp_f32_e32 v8, v8
	v_rcp_f32_e32 v25, v25
	v_add_f32_e32 v7, 1.0, v7
	v_max_f32_e32 v87, 0xda24260, v87
	v_mul_f32_e32 v6, v90, v6
	v_mul_f32_e32 v90, v7, v87
	v_add_f32_e32 v26, v26, v80
	v_mul_f32_e32 v7, v7, v90
	v_fma_f32 v90, -v24, v24, 1.0
	v_exp_f32_e32 v26, v26
	v_add_f32_e32 v8, 1.0, v8
	v_max_f32_e32 v90, 0xda24260, v90
	v_mul_f32_e32 v25, v84, v25
	v_rsq_f32_e32 v7, v7
	v_mul_f32_e32 v91, v8, v90
	v_add_f32_e32 v9, v9, v81
	v_exp_f32_e32 v25, v25
	v_add_f32_e32 v27, v27, v80
	v_mul_f32_e32 v8, v8, v91
	v_exp_f32_e32 v9, v9
	v_exp_f32_e32 v27, v27
	v_rsq_f32_e32 v8, v8
	v_add_f32_e32 v26, 1.0, v26
	v_rcp_f32_e32 v26, v26
	v_mul_f32_e32 v7, v87, v7
	v_fma_f32 v87, -v25, v25, 1.0
	v_add_f32_e32 v9, 1.0, v9
	v_max_f32_e32 v87, 0xda24260, v87
	v_add_f32_e32 v27, 1.0, v27
	v_mul_f32_e32 v8, v90, v8
	v_mul_f32_e32 v90, v9, v87
	v_rcp_f32_e32 v27, v27
	v_add_f32_e32 v28, v28, v80
	v_mul_f32_e32 v9, v9, v90
	v_mul_f32_e32 v26, v84, v26
	v_exp_f32_e32 v28, v28
	v_rsq_f32_e32 v9, v9
	v_add_f32_e32 v10, v10, v81
	v_exp_f32_e32 v26, v26
	v_exp_f32_e32 v10, v10
	v_mul_f32_e32 v27, v84, v27
	v_add_f32_e32 v11, v11, v81
	v_exp_f32_e32 v27, v27
	v_add_f32_e32 v28, 1.0, v28
	v_mul_f32_e32 v9, v87, v9
	v_fma_f32 v87, -v26, v26, 1.0
	v_exp_f32_e32 v11, v11
	v_rcp_f32_e32 v28, v28
	v_add_f32_e32 v10, 1.0, v10
	v_max_f32_e32 v87, 0xda24260, v87
	v_mul_f32_e32 v90, v10, v87
	v_add_f32_e32 v29, v29, v80
	v_mul_f32_e32 v10, v10, v90
	v_fma_f32 v90, -v27, v27, 1.0
	v_exp_f32_e32 v29, v29
	v_add_f32_e32 v11, 1.0, v11
	v_max_f32_e32 v90, 0xda24260, v90
	v_mul_f32_e32 v28, v84, v28
	v_rsq_f32_e32 v10, v10
	v_mul_f32_e32 v91, v11, v90
	v_add_f32_e32 v12, v12, v81
	v_exp_f32_e32 v28, v28
	v_add_f32_e32 v30, v30, v80
	v_mul_f32_e32 v11, v11, v91
	v_exp_f32_e32 v12, v12
	v_exp_f32_e32 v30, v30
	v_rsq_f32_e32 v11, v11
	v_add_f32_e32 v29, 1.0, v29
	v_rcp_f32_e32 v29, v29
	v_add_f32_e32 v31, v31, v80
	v_mul_f32_e32 v10, v87, v10
	v_fma_f32 v87, -v28, v28, 1.0
	v_exp_f32_e32 v31, v31
	v_add_f32_e32 v12, 1.0, v12
	v_max_f32_e32 v87, 0xda24260, v87
	v_add_f32_e32 v30, 1.0, v30
	v_mul_f32_e32 v11, v90, v11
	v_mul_f32_e32 v90, v12, v87
	v_rcp_f32_e32 v30, v30
	v_add_f32_e32 v19, v19, v80
	v_mul_f32_e32 v12, v12, v90
	v_mul_f32_e32 v29, v84, v29
	v_exp_f32_e32 v19, v19
	v_rsq_f32_e32 v12, v12
	v_add_f32_e32 v13, v13, v81
	v_exp_f32_e32 v29, v29
	v_add_f32_e32 v31, 1.0, v31
	v_exp_f32_e32 v13, v13
	v_rcp_f32_e32 v31, v31
	v_add_f32_e32 v18, v18, v80
	v_mul_f32_e32 v30, v84, v30
	v_exp_f32_e32 v18, v18
	v_add_f32_e32 v16, v16, v80
	v_add_f32_e32 v14, v14, v81
	v_exp_f32_e32 v30, v30
	v_add_f32_e32 v19, 1.0, v19
	v_exp_f32_e32 v16, v16
	v_mul_f32_e32 v12, v87, v12
	v_fma_f32 v87, -v29, v29, 1.0
	v_exp_f32_e32 v14, v14
	v_rcp_f32_e32 v19, v19
	v_add_f32_e32 v17, v17, v80
; template <int PASS>
; __device__ __forceinline__ void lru_item(Frame& F, const LAS bf16* lw, const LAS float* prm, const LAS float* cwl, LAS float* xs, LAS unsigned char* pf, int head, int item, int nitem) {
;     ...
;             {
;                 const float br = prm[(d * 3 + 0) * 64 + chl], bi = prm[(d * 3 + 1) * 64 + chl], c8 = prm[(d * 3 + 2) * 64 + chl];
; #pragma unroll
;                 for (int rg = 0; rg < 16; ++rg) {
;                     const float rr = __builtin_amdgcn_rcpf(1.f + __builtin_amdgcn_exp2f(acc[0][rg] + br)), ei = 1.f + __builtin_amdgcn_exp2f(acc[1][rg] + bi);
;                     const float a = __builtin_amdgcn_exp2f(c8 * rr), om = fmaxf(fmaf(-a, a, 1.f), 1e-30f);
;                     av[rg] = a; bv[rg] = (om * __builtin_amdgcn_rsqf(om * ei * ei)) * xd[ct][rg];
;                 }
;             }
;             float hl[16], cp[16], sA[4], sB[4];
; #pragma unroll
;             for (int q4 = 0; q4 < 4; ++q4) {
;                 if (d == 0) {
;                     hl[4 * q4] = bv[4 * q4]; cp[4 * q4] = av[4 * q4];
; #pragma unroll
;                     for (int i = 1; i < 4; ++i) { hl[4 * q4 + i] = av[4 * q4 + i] * hl[4 * q4 + i - 1] + bv[4 * q4 + i]; cp[4 * q4 + i] = av[4 * q4 + i] * cp[4 * q4 + i - 1]; }
;                     sA[q4] = cp[4 * q4 + 3]; sB[q4] = hl[4 * q4 + 3];
;                 } else {
;                     hl[4 * q4 + 3] = bv[4 * q4 + 3]; cp[4 * q4 + 3] = av[4 * q4 + 3];
; #pragma unroll
;                     for (int i = 2; i >= 0; --i) { hl[4 * q4 + i] = av[4 * q4 + i] * hl[4 * q4 + i + 1] + bv[4 * q4 + i]; cp[4 * q4 + i] = av[4 * q4 + i] * cp[4 * q4 + i + 1]; }
;                     sA[q4] = cp[4 * q4]; sB[q4] = hl[4 * q4];
;                 }
;             }
;             float Ae[4], Be[4], Ao[4], Bo[4];
; #pragma unroll
;             for (int q4 = 0; q4 < 4; ++q4) {
;                 const float oA = shx(sA[q4], 32, lane), oB = shx(sB[q4], 32, lane);
;                 Ae[q4] = hh ? oA : sA[q4]; Be[q4] = hh ? oB : sB[q4]; Ao[q4] = hh ? sA[q4] : oA; Bo[q4] = hh ? sB[q4] : oB;
;             }
;             if (PASS == 1) {
;                 float c = 0.f, P = 1.f;
;                 if (d == 0) {
; #pragma unroll
;                     for (int q4 = 0; q4 < 4; ++q4) { c = Ae[q4] * c + Be[q4]; c = Ao[q4] * c + Bo[q4]; P *= Ae[q4] * Ao[q4]; } }
;                 else {
; #pragma unroll
	v_add_f32_e32 v13, 1.0, v13
	v_max_f32_e32 v87, 0xda24260, v87
	v_mul_f32_e32 v31, v84, v31
	v_exp_f32_e32 v17, v17
	v_mul_f32_e32 v90, v13, v87
	v_add_f32_e32 v15, v15, v81
	v_exp_f32_e32 v31, v31
	v_add_f32_e32 v18, 1.0, v18
	v_mul_f32_e32 v13, v13, v90
	v_fma_f32 v90, -v30, v30, 1.0
	v_exp_f32_e32 v15, v15
	v_rcp_f32_e32 v18, v18
	v_add_f32_e32 v16, 1.0, v16
	v_add_f32_e32 v14, 1.0, v14
	v_max_f32_e32 v90, 0xda24260, v90
	v_mul_f32_e32 v19, v84, v19
	v_rcp_f32_e32 v16, v16
	v_rsq_f32_e32 v13, v13
	v_mul_f32_e32 v91, v14, v90
	v_exp_f32_e32 v19, v19
	v_add_f32_e32 v3, v3, v81
	v_add_f32_e32 v17, 1.0, v17
	v_mul_f32_e32 v14, v14, v91
	v_fma_f32 v91, -v31, v31, 1.0
	v_exp_f32_e32 v3, v3
	v_rcp_f32_e32 v17, v17
	v_rsq_f32_e32 v14, v14
	v_add_f32_e32 v15, 1.0, v15
	v_max_f32_e32 v91, 0xda24260, v91
	v_mul_f32_e32 v18, v84, v18
	v_mul_f32_e32 v92, v15, v91
	v_exp_f32_e32 v18, v18
	v_add_f32_e32 v2, v2, v81
	v_mul_f32_e32 v16, v84, v16
	v_mul_f32_e32 v15, v15, v92
	v_mul_f32_e32 v13, v87, v13
	v_fma_f32 v87, -v19, v19, 1.0
	v_exp_f32_e32 v2, v2
	v_exp_f32_e32 v16, v16
	v_add_f32_e32 v0, v0, v81
	v_rsq_f32_e32 v15, v15
	v_max_f32_e32 v87, 0xda24260, v87
	v_add_f32_e32 v3, 1.0, v3
	v_mul_f32_e32 v17, v84, v17
	v_exp_f32_e32 v0, v0
	v_mul_f32_e32 v14, v90, v14
	v_mul_f32_e32 v90, v3, v87
	v_exp_f32_e32 v17, v17
	v_add_f32_e32 v1, v1, v81
	v_mul_f32_e32 v3, v3, v90
	v_fma_f32 v90, -v18, v18, 1.0
	v_exp_f32_e32 v1, v1
	v_max_f32_e32 v90, 0xda24260, v90
	v_add_f32_e32 v2, 1.0, v2
	v_fma_f32 v81, -v16, v16, 1.0
	v_mul_f32_e32 v15, v91, v15
	v_mul_f32_e32 v91, v2, v90
	v_max_f32_e32 v81, 0xda24260, v81
	v_add_f32_e32 v0, 1.0, v0
	v_mul_f32_e32 v2, v2, v91
	v_fma_f32 v91, -v17, v17, 1.0
	v_mul_f32_e32 v84, v0, v81
	v_max_f32_e32 v80, 0xda24260, v91
	v_add_f32_e32 v1, 1.0, v1
	v_mul_f32_e32 v0, v0, v84
	v_mul_f32_e32 v91, v1, v80
	v_rsq_f32_e32 v0, v0
	v_mul_f32_e32 v1, v1, v91
	v_rsq_f32_e32 v1, v1
	v_rsq_f32_e32 v2, v2
	v_mul_f32_e32 v0, v81, v0
	v_mul_f32_e32 v0, v59, v0
	v_mul_f32_e32 v1, v80, v1
	v_mul_f32_e32 v0, v17, v0
	v_fmac_f32_e32 v0, v65, v1
	v_mul_f32_e32 v2, v90, v2
	v_mul_f32_e32 v0, v18, v0
	v_mul_f32_e32 v4, v51, v4
	v_fmac_f32_e32 v0, v69, v2
	v_mul_f32_e32 v2, v19, v0
	v_mul_f32_e32 v0, v21, v4
	v_fmac_f32_e32 v0, v61, v5
	v_rsq_f32_e32 v3, v3
	v_mul_f32_e32 v0, v22, v0
	v_mul_f32_e32 v8, v53, v8
	v_fmac_f32_e32 v0, v67, v6
	v_mul_f32_e32 v4, v23, v0
	v_mul_f32_e32 v0, v25, v8
	v_mul_f32_e32 v1, v16, v17
	v_fmac_f32_e32 v0, v57, v9
	v_mul_f32_e32 v3, v87, v3
	v_mul_f32_e32 v1, v18, v1
	v_mul_f32_e32 v0, v26, v0
	v_mul_f32_e32 v12, v49, v12
	v_fmac_f32_e32 v2, v73, v3
	v_mul_f32_e32 v3, v19, v1
	v_mul_f32_e32 v1, v20, v21
	v_fmac_f32_e32 v0, v63, v10
	v_mul_f32_e32 v1, v22, v1
	v_mul_f32_e32 v6, v27, v0
	v_mul_f32_e32 v0, v29, v12
	v_mul_f32_e32 v5, v23, v1
	v_mul_f32_e32 v1, v24, v25
	v_fmac_f32_e32 v0, v55, v13
	v_mul_f32_e32 v1, v26, v1
	v_mul_f32_e32 v0, v30, v0
	v_fmac_f32_e32 v4, v79, v7
	v_mul_f32_e32 v7, v27, v1
	v_mul_f32_e32 v1, v28, v29
	v_fmac_f32_e32 v0, v71, v14
	v_mul_f32_e32 v1, v30, v1
	v_mul_f32_e32 v8, v31, v0
	v_fmac_f32_e32 v6, v77, v11
	v_fmac_f32_e32 v8, v75, v15
	v_mul_f32_e32 v9, v31, v1
	s_nop 1
	v_permlane32_swap_b32 v3, v16
	v_permlane32_swap_b32 v2, v15
	v_permlane32_swap_b32 v5, v14
	v_permlane32_swap_b32 v4, v13
	v_permlane32_swap_b32 v7, v12
	v_permlane32_swap_b32 v6, v11
	v_permlane32_swap_b32 v9, v10
	v_permlane32_swap_b32 v8, v1
	v_or_b32_e32 v0, 32, v110
	v_lshl_or_b32 v84, v0, 3, s79
	s_and_saveexec_b64 s[12:13], vcc
	s_cbranch_execz .LBB0_706
	v_fmac_f32_e32 v2, 0, v3
	s_waitcnt lgkmcnt(0)
	v_fmac_f32_e32 v15, v2, v16
	v_fmac_f32_e32 v4, v5, v15
	v_fmac_f32_e32 v13, v4, v14
	v_mul_f32_e32 v0, v3, v16
	v_mul_f32_e32 v17, v5, v14
	v_fmac_f32_e32 v6, v7, v13
	v_mul_f32_e32 v0, v0, v17
	v_mul_f32_e32 v17, v7, v12
	v_fmac_f32_e32 v11, v6, v12
	s_lshl_b64 s[10:11], s[10:11], 2
	v_mul_f32_e32 v0, v17, v0
	v_mul_f32_e32 v17, v9, v10
	v_fmac_f32_e32 v8, v9, v11
	s_add_u32 s10, s19, s10
	v_mul_f32_e32 v0, v17, v0
	v_fmac_f32_e32 v1, v8, v10
	s_addc_u32 s11, s30, s11
	global_store_dwordx2 v84, v[0:1], s[10:11]
.LBB0_706:
	s_or_b64 exec, exec, s[12:13]
	s_waitcnt lgkmcnt(0)
	ds_read_b128 v[0:3], v85 offset:18432
	ds_read_b128 v[4:7], v85 offset:18464
	s_addk_i32 s8, 0x208
	s_ashr_i32 s9, s8, 31
	s_lshl_b64 s[8:9], s[8:9], 11
	s_waitcnt lgkmcnt(0)
	v_mfma_f32_32x32x16_bf16 v[16:31], v[32:35], v[0:3], 0
	v_mfma_f32_32x32x16_bf16 v[16:31], v[36:39], v[4:7], v[16:31]
	ds_read_b128 v[0:3], v85 offset:18496
	ds_read_b128 v[4:7], v85 offset:18528
	s_waitcnt lgkmcnt(0)
	v_mfma_f32_32x32x16_bf16 v[16:31], v[40:43], v[0:3], v[16:31]
	ds_read_b128 v[0:3], v85 offset:27648
	ds_read_b128 v[90:93], v85 offset:27680
	v_mfma_f32_32x32x16_bf16 v[16:31], v[44:47], v[4:7], v[16:31]
	s_waitcnt lgkmcnt(0)
	v_mfma_f32_32x32x16_bf16 v[0:15], v[32:35], v[0:3], 0
	v_mfma_f32_32x32x16_bf16 v[0:15], v[36:39], v[90:93], v[0:15]
	ds_read_b128 v[90:93], v85 offset:27712
	ds_read2st64_b32 v[80:81], v83 offset0:147 offset1:148
	ds_read_b128 v[94:97], v85 offset:27744
	ds_read_b32 v87, v83 offset:38144
	s_waitcnt lgkmcnt(0)
; template <int PASS>
; __device__ __forceinline__ void lru_item(Frame& F, const LAS bf16* lw, const LAS float* prm, const LAS float* cwl, LAS float* xs, LAS unsigned char* pf, int head, int item, int nitem) {
;     ...
;             {
;                 const float br = prm[(d * 3 + 0) * 64 + chl], bi = prm[(d * 3 + 1) * 64 + chl], c8 = prm[(d * 3 + 2) * 64 + chl];
; #pragma unroll
;                 for (int rg = 0; rg < 16; ++rg) {
;                     const float rr = __builtin_amdgcn_rcpf(1.f + __builtin_amdgcn_exp2f(acc[0][rg] + br)), ei = 1.f + __builtin_amdgcn_exp2f(acc[1][rg] + bi);
;                     const float a = __builtin_amdgcn_exp2f(c8 * rr), om = fmaxf(fmaf(-a, a, 1.f), 1e-30f);
;                     av[rg] = a; bv[rg] = (om * __builtin_amdgcn_rsqf(om * ei * ei)) * xd[ct][rg];
;                 }
;             }
	s_nop 3
	v_add_f32_e32 v20, v20, v80
	v_exp_f32_e32 v20, v20
	v_add_f32_e32 v22, v22, v80
	v_exp_f32_e32 v22, v22
	v_mfma_f32_32x32x16_bf16 v[0:15], v[40:43], v[90:93], v[0:15]
	v_add_f32_e32 v20, 1.0, v20
	v_rcp_f32_e32 v20, v20
	v_add_f32_e32 v18, v18, v80
	v_exp_f32_e32 v18, v18
	v_add_f32_e32 v16, v16, v80
	v_mul_f32_e32 v20, v87, v20
	v_exp_f32_e32 v90, v20
	v_mfma_f32_32x32x16_bf16 v[0:15], v[44:47], v[94:97], v[0:15]
	v_add_f32_e32 v20, v21, v80
	v_exp_f32_e32 v20, v20
	v_fma_f32 v21, -v90, v90, 1.0
	v_max_f32_e32 v21, 0xda24260, v21
	v_add_f32_e32 v18, 1.0, v18
	v_add_f32_e32 v20, 1.0, v20
	v_rcp_f32_e32 v20, v20
	s_nop 4
	v_add_f32_e32 v4, v4, v81
	v_exp_f32_e32 v4, v4
	v_add_f32_e32 v5, v5, v81
	v_mul_f32_e32 v20, v87, v20
	v_exp_f32_e32 v92, v20
	v_add_f32_e32 v4, 1.0, v4
	v_mul_f32_e32 v91, v4, v21
	v_exp_f32_e32 v5, v5
	v_mul_f32_e32 v4, v4, v91
	v_rsq_f32_e32 v4, v4
	v_fma_f32 v20, -v92, v92, 1.0
	v_add_f32_e32 v5, 1.0, v5
	v_max_f32_e32 v20, 0xda24260, v20
	v_mul_f32_e32 v91, v5, v20
	v_mul_f32_e32 v5, v5, v91
	v_mul_f32_e32 v91, v21, v4
	v_add_f32_e32 v4, 1.0, v22
	v_rcp_f32_e32 v4, v4
	v_rsq_f32_e32 v5, v5
	v_add_f32_e32 v7, v7, v81
	v_exp_f32_e32 v7, v7
	v_mul_f32_e32 v4, v87, v4
	v_exp_f32_e32 v93, v4
	v_add_f32_e32 v4, v23, v80
	v_exp_f32_e32 v4, v4
	v_mul_f32_e32 v22, v20, v5
	v_add_f32_e32 v5, v6, v81
	v_exp_f32_e32 v5, v5
	v_add_f32_e32 v4, 1.0, v4
	v_rcp_f32_e32 v4, v4
	v_fma_f32 v6, -v93, v93, 1.0
	v_add_f32_e32 v5, 1.0, v5
	v_max_f32_e32 v6, 0xda24260, v6
	v_mul_f32_e32 v4, v87, v4
	v_exp_f32_e32 v23, v4
	v_mul_f32_e32 v20, v5, v6
	v_mul_f32_e32 v4, v5, v20
	v_add_f32_e32 v20, v24, v80
	v_rsq_f32_e32 v5, v4
	v_add_f32_e32 v4, 1.0, v7
	v_fma_f32 v7, -v23, v23, 1.0
	v_exp_f32_e32 v20, v20
	v_max_f32_e32 v7, 0xda24260, v7
	v_mul_f32_e32 v21, v4, v7
	v_mul_f32_e32 v4, v4, v21
	v_add_f32_e32 v20, 1.0, v20
	v_rsq_f32_e32 v21, v4
	v_add_f32_e32 v4, v8, v81
	v_rcp_f32_e32 v20, v20
	v_exp_f32_e32 v8, v4
	v_mul_f32_e32 v24, v6, v5
	v_mul_f32_e32 v5, v7, v21
	v_mul_f32_e32 v4, v87, v20
	v_add_f32_e32 v6, 1.0, v8
	v_add_f32_e32 v8, v25, v80
	v_exp_f32_e32 v4, v4
	v_exp_f32_e32 v8, v8
	v_mul_f32_e32 v25, v78, v5
	v_add_f32_e32 v11, v11, v81
	v_fma_f32 v7, -v4, v4, 1.0
	v_add_f32_e32 v8, 1.0, v8
	v_max_f32_e32 v7, 0xda24260, v7
	v_rcp_f32_e32 v8, v8
	v_mul_f32_e32 v20, v6, v7
	v_mul_f32_e32 v6, v6, v20
	v_rsq_f32_e32 v20, v6
	v_add_f32_e32 v6, v9, v81
	v_exp_f32_e32 v9, v6
	v_mul_f32_e32 v6, v87, v8
	v_exp_f32_e32 v6, v6
	v_add_f32_e32 v8, v26, v80
	v_exp_f32_e32 v8, v8
	v_mul_f32_e32 v78, v7, v20
	v_fma_f32 v7, -v6, v6, 1.0
	v_add_f32_e32 v5, 1.0, v9
	v_max_f32_e32 v7, 0xda24260, v7
	v_mul_f32_e32 v9, v5, v7
	v_mul_f32_e32 v5, v5, v9
	v_add_f32_e32 v8, 1.0, v8
	v_add_f32_e32 v9, v10, v81
	v_add_f32_e32 v10, v27, v80
	v_rcp_f32_e32 v8, v8
	v_exp_f32_e32 v10, v10
	v_exp_f32_e32 v9, v9
	v_exp_f32_e32 v11, v11
	v_mul_f32_e32 v8, v87, v8
	v_add_f32_e32 v10, 1.0, v10
	v_exp_f32_e32 v8, v8
	v_rcp_f32_e32 v10, v10
	v_add_f32_e32 v9, 1.0, v9
	v_rsq_f32_e32 v5, v5
	v_fma_f32 v20, -v8, v8, 1.0
	v_mul_f32_e32 v10, v87, v10
	v_max_f32_e32 v21, 0xda24260, v20
	v_exp_f32_e32 v20, v10
	v_add_f32_e32 v10, 1.0, v11
	v_mul_f32_e32 v26, v9, v21
	v_mul_f32_e32 v9, v9, v26
	v_fma_f32 v11, -v20, v20, 1.0
	v_max_f32_e32 v11, 0xda24260, v11
	v_mul_f32_e32 v26, v10, v11
	v_mul_f32_e32 v10, v10, v26
	v_add_f32_e32 v26, v28, v80
	v_exp_f32_e32 v26, v26
	v_rsq_f32_e32 v10, v10
	v_mul_f32_e32 v27, v7, v5
	v_rsq_f32_e32 v9, v9
	v_add_f32_e32 v7, 1.0, v26
	v_rcp_f32_e32 v7, v7
	v_mul_f32_e32 v5, v11, v10
	v_mul_f32_e32 v26, v76, v5
	v_add_f32_e32 v5, v12, v81
	v_mul_f32_e32 v28, v21, v9
	v_exp_f32_e32 v9, v5
	v_mul_f32_e32 v5, v87, v7
	v_add_f32_e32 v7, v29, v80
	v_exp_f32_e32 v7, v7
	v_exp_f32_e32 v5, v5
	v_add_f32_e32 v12, v13, v81
	v_exp_f32_e32 v12, v12
	v_add_f32_e32 v7, 1.0, v7
	v_rcp_f32_e32 v7, v7
	v_fma_f32 v10, -v5, v5, 1.0
	v_add_f32_e32 v9, 1.0, v9
	v_max_f32_e32 v10, 0xda24260, v10
	v_mul_f32_e32 v7, v87, v7
	v_exp_f32_e32 v7, v7
	v_mul_f32_e32 v11, v9, v10
	v_add_f32_e32 v13, v30, v80
	v_mul_f32_e32 v9, v9, v11
	v_exp_f32_e32 v13, v13
	v_rsq_f32_e32 v11, v9
	v_add_f32_e32 v9, 1.0, v12
	v_fma_f32 v12, -v7, v7, 1.0
	v_max_f32_e32 v12, 0xda24260, v12
	v_mul_f32_e32 v21, v9, v12
	v_mul_f32_e32 v9, v9, v21
	v_add_f32_e32 v13, 1.0, v13
	v_rcp_f32_e32 v13, v13
	v_rsq_f32_e32 v21, v9
	v_add_f32_e32 v9, v14, v81
	v_exp_f32_e32 v14, v9
	v_mul_f32_e32 v9, v87, v13
	v_mul_f32_e32 v13, v12, v21
	v_add_f32_e32 v12, v31, v80
	v_exp_f32_e32 v12, v12
	v_exp_f32_e32 v9, v9
	v_mul_f32_e32 v29, v10, v11
	v_add_f32_e32 v10, 1.0, v14
	v_add_f32_e32 v12, 1.0, v12
	v_rcp_f32_e32 v12, v12
	v_fma_f32 v11, -v9, v9, 1.0
	v_max_f32_e32 v11, 0xda24260, v11
	v_mul_f32_e32 v14, v10, v11
	v_mul_f32_e32 v10, v10, v14
	v_mul_f32_e32 v12, v87, v12
	v_rsq_f32_e32 v10, v10
	v_add_f32_e32 v14, v15, v81
	v_exp_f32_e32 v21, v12
	v_exp_f32_e32 v14, v14
	v_add_f32_e32 v12, v19, v80
	v_exp_f32_e32 v12, v12
	v_mul_f32_e32 v15, v11, v10
	v_fma_f32 v11, -v21, v21, 1.0
	v_add_f32_e32 v10, 1.0, v14
	v_max_f32_e32 v11, 0xda24260, v11
	v_add_f32_e32 v12, 1.0, v12
	v_mul_f32_e32 v14, v10, v11
	v_rcp_f32_e32 v12, v12
	v_mul_f32_e32 v10, v10, v14
	v_rsq_f32_e32 v10, v10
	v_add_f32_e32 v3, v3, v81
	v_mul_f32_e32 v12, v87, v12
	v_exp_f32_e32 v12, v12
	v_mul_f32_e32 v10, v11, v10
	v_add_f32_e32 v11, v17, v80
	v_exp_f32_e32 v3, v3
	v_exp_f32_e32 v11, v11
	v_rcp_f32_e32 v18, v18
	v_fma_f32 v14, -v12, v12, 1.0
	v_exp_f32_e32 v16, v16
	v_max_f32_e32 v14, 0xda24260, v14
	v_add_f32_e32 v3, 1.0, v3
	v_add_f32_e32 v11, 1.0, v11
	v_mul_f32_e32 v19, v3, v14
	v_rcp_f32_e32 v11, v11
	v_mul_f32_e32 v3, v3, v19
; #define LAS __attribute__((address_space(3)))
; template <int PASS>
; __device__ __forceinline__ void lru_item(Frame& F, const LAS bf16* lw, const LAS float* prm, const LAS float* cwl, LAS float* xs, LAS unsigned char* pf, int head, int item, int nitem) {
;     ...
;     for (int d = 0; d < 2; ++d) {
; #pragma unroll
;         for (int ct = 0; ct < 2; ++ct) {
;             f32x16 acc[2];
; #pragma unroll
;             for (int gt = 0; gt < 2; ++gt) {
;                 f32x16 a; for (int i = 0; i < 16; ++i) a[i] = 0.f;
;                 const LAS bf16* wb = lw + ((d * 2 + gt) * 64 + t + 32 * ct) * LRU_WROW + 8 * hh;
; #pragma unroll
;     ...
;             float hl[16], cp[16], sA[4], sB[4];
; #pragma unroll
;             for (int q4 = 0; q4 < 4; ++q4) {
;                 if (d == 0) {
;                     hl[4 * q4] = bv[4 * q4]; cp[4 * q4] = av[4 * q4];
; #pragma unroll
;                     for (int i = 1; i < 4; ++i) { hl[4 * q4 + i] = av[4 * q4 + i] * hl[4 * q4 + i - 1] + bv[4 * q4 + i]; cp[4 * q4 + i] = av[4 * q4 + i] * cp[4 * q4 + i - 1]; }
;                     sA[q4] = cp[4 * q4 + 3]; sB[q4] = hl[4 * q4 + 3];
;                 } else {
;                     hl[4 * q4 + 3] = bv[4 * q4 + 3]; cp[4 * q4 + 3] = av[4 * q4 + 3];
; #pragma unroll
;                     for (int i = 2; i >= 0; --i) { hl[4 * q4 + i] = av[4 * q4 + i] * hl[4 * q4 + i + 1] + bv[4 * q4 + i]; cp[4 * q4 + i] = av[4 * q4 + i] * cp[4 * q4 + i + 1]; }
;                     sA[q4] = cp[4 * q4]; sB[q4] = hl[4 * q4];
;                 }
;             }
;             float Ae[4], Be[4], Ao[4], Bo[4];
; #pragma unroll
;             for (int q4 = 0; q4 < 4; ++q4) {
;                 const float oA = shx(sA[q4], 32, lane), oB = shx(sB[q4], 32, lane);
;                 Ae[q4] = hh ? oA : sA[q4]; Be[q4] = hh ? oB : sB[q4]; Ao[q4] = hh ? sA[q4] : oA; Bo[q4] = hh ? sB[q4] : oB;
;             }
;             if (PASS == 1) {
;                 float c = 0.f, P = 1.f;
;                 if (d == 0) {
; #pragma unroll
;                     for (int q4 = 0; q4 < 4; ++q4) { c = Ae[q4] * c + Be[q4]; c = Ao[q4] * c + Bo[q4]; P *= Ae[q4] * Ao[q4]; } }
;                 else {
; #pragma unroll
;     ...
;                 if (hh == 0) { float* o = (float*)(F.ws + WS_PL) + ((size_t)((b * 2 + d) * NQ + q) * 1024 + ch) * 2; o[0] = P; o[1] = c; }
	v_mul_f32_e32 v19, v74, v10
	v_mul_f32_e32 v10, v87, v18
	v_rsq_f32_e32 v3, v3
	v_exp_f32_e32 v10, v10
	v_add_f32_e32 v2, v2, v81
	v_add_f32_e32 v16, 1.0, v16
	v_exp_f32_e32 v2, v2
	v_rcp_f32_e32 v16, v16
	v_mul_f32_e32 v11, v87, v11
	v_exp_f32_e32 v11, v11
	v_add_f32_e32 v1, v1, v81
	v_mul_f32_e32 v3, v14, v3
	v_fma_f32 v14, -v10, v10, 1.0
	v_exp_f32_e32 v1, v1
	v_max_f32_e32 v14, 0xda24260, v14
	v_add_f32_e32 v2, 1.0, v2
	v_mul_f32_e32 v16, v87, v16
	v_mul_f32_e32 v17, v2, v14
	v_exp_f32_e32 v16, v16
	v_add_f32_e32 v0, v0, v81
	v_mul_f32_e32 v2, v2, v17
	v_fma_f32 v17, -v11, v11, 1.0
	v_exp_f32_e32 v0, v0
	v_max_f32_e32 v17, 0xda24260, v17
	v_add_f32_e32 v1, 1.0, v1
	v_mul_f32_e32 v18, v1, v17
	v_rsq_f32_e32 v2, v2
	v_mul_f32_e32 v1, v1, v18
	v_fma_f32 v18, -v16, v16, 1.0
	v_max_f32_e32 v18, 0xda24260, v18
	v_add_f32_e32 v0, 1.0, v0
	v_rsq_f32_e32 v1, v1
	v_mul_f32_e32 v30, v0, v18
	v_mul_f32_e32 v0, v0, v30
	v_mul_f32_e32 v3, v72, v3
	v_rsq_f32_e32 v0, v0
	v_mul_f32_e32 v2, v14, v2
	v_mul_f32_e32 v3, v10, v3
	v_fmac_f32_e32 v3, v68, v2
	v_mul_f32_e32 v1, v17, v1
	v_mul_f32_e32 v3, v11, v3
	v_fmac_f32_e32 v3, v64, v1
	v_mul_f32_e32 v0, v18, v0
	v_mul_f32_e32 v1, v16, v3
	v_fmac_f32_e32 v1, v58, v0
	v_mul_f32_e32 v0, v93, v25
	v_fmac_f32_e32 v0, v66, v24
	v_mul_f32_e32 v0, v92, v0
	v_fmac_f32_e32 v0, v60, v22
	v_mul_f32_e32 v2, v12, v10
	v_mul_f32_e32 v10, v90, v0
	v_mul_f32_e32 v0, v8, v26
	v_fmac_f32_e32 v0, v62, v28
	v_mul_f32_e32 v0, v6, v0
	v_fmac_f32_e32 v0, v56, v27
	v_mul_f32_e32 v12, v4, v0
	v_mul_f32_e32 v0, v9, v19
	v_fmac_f32_e32 v0, v70, v15
	v_mul_f32_e32 v2, v11, v2
	v_mul_f32_e32 v0, v7, v0
	v_mul_f32_e32 v3, v16, v2
	v_mul_f32_e32 v2, v23, v93
	v_fmac_f32_e32 v0, v54, v13
	v_pk_mul_f32 v[8:9], v[20:21], v[8:9]
	v_mul_f32_e32 v2, v92, v2
	v_mul_f32_e32 v13, v5, v0
	v_pk_mul_f32 v[6:7], v[6:7], v[8:9]
	v_fmac_f32_e32 v10, v50, v91
	v_mul_f32_e32 v11, v90, v2
	v_fmac_f32_e32 v12, v52, v78
	v_fmac_f32_e32 v13, v48, v29
	v_pk_mul_f32 v[6:7], v[4:5], v[6:7]
	s_nop 1
	v_permlane32_swap_b32 v3, v4
	v_permlane32_swap_b32 v1, v5
	v_permlane32_swap_b32 v11, v15
	v_permlane32_swap_b32 v10, v14
	v_permlane32_swap_b32 v6, v8
	v_permlane32_swap_b32 v12, v16
	v_permlane32_swap_b32 v7, v9
	v_permlane32_swap_b32 v13, v17
	s_and_saveexec_b64 s[10:11], vcc
	s_cbranch_execz .LBB0_708
	s_waitcnt lgkmcnt(0)
	v_fmac_f32_e32 v17, 0, v9
	v_fmac_f32_e32 v13, v7, v17
	v_fmac_f32_e32 v16, v13, v8
	v_fmac_f32_e32 v12, v6, v16
	v_pk_mul_f32 v[18:19], v[6:7], v[8:9]
	v_fmac_f32_e32 v14, v12, v15
	v_mul_f32_e32 v2, v11, v15
	v_fmac_f32_e32 v10, v11, v14
	s_lshl_b64 s[12:13], s[8:9], 2
	v_pk_mul_f32 v[8:9], v[18:19], v[18:19] op_sel:[0,1] op_sel_hi:[1,0]
	v_mul_f32_e32 v0, v3, v4
	v_fmac_f32_e32 v5, v10, v4
	s_add_u32 s12, s19, s12
	v_mov_b32_e32 v4, v8
	v_pk_mul_f32 v[8:9], v[2:3], v[8:9]
	s_addc_u32 s13, s30, s13
	v_pk_mul_f32 v[8:9], v[0:1], v[8:9]
	v_pk_fma_f32 v[0:1], v[2:3], v[4:5], v[0:1]
	v_lshl_add_u64 v[6:7], v[88:89], 2, s[12:13]
	v_mov_b32_e32 v9, v1
	global_store_dwordx2 v[6:7], v[8:9], off
.LBB0_708:
	s_or_b64 exec, exec, s[10:11]
	ds_read_b128 v[0:3], v85 offset:23040
	ds_read_b32 v48, v83 offset:38272
	s_waitcnt lgkmcnt(0)
	v_mfma_f32_32x32x16_bf16 v[16:31], v[32:35], v[0:3], 0
	ds_read_b128 v[0:3], v85 offset:23072
	ds_read_b128 v[4:7], v85 offset:23104
	s_waitcnt lgkmcnt(0)
	v_mfma_f32_32x32x16_bf16 v[16:31], v[36:39], v[0:3], v[16:31]
	v_mfma_f32_32x32x16_bf16 v[16:31], v[40:43], v[4:7], v[16:31]
	ds_read_b128 v[0:3], v85 offset:23136
	ds_read_b128 v[4:7], v85 offset:32256
	s_waitcnt lgkmcnt(0)
	v_mfma_f32_32x32x16_bf16 v[16:31], v[44:47], v[0:3], v[16:31]
	v_mfma_f32_32x32x16_bf16 v[0:15], v[32:35], v[4:7], 0
	ds_read_b128 v[32:35], v85 offset:32288
	ds_read_b128 v[90:93], v85 offset:32320
	s_waitcnt lgkmcnt(0)
	v_mfma_f32_32x32x16_bf16 v[0:15], v[36:39], v[32:35], v[0:15]
	ds_read2st64_b32 v[32:33], v86 offset0:147 offset1:148
	ds_read_b128 v[34:37], v85 offset:32352
	s_waitcnt lgkmcnt(0)
	s_nop 3
	v_add_f32_e32 v20, v20, v32
	v_exp_f32_e32 v20, v20
	v_mfma_f32_32x32x16_bf16 v[0:15], v[40:43], v[90:93], v[0:15]
	v_add_f32_e32 v22, v22, v32
	v_exp_f32_e32 v22, v22
	v_add_f32_e32 v20, 1.0, v20
	v_rcp_f32_e32 v20, v20
	v_add_f32_e32 v18, v18, v32
	v_exp_f32_e32 v18, v18
	v_add_f32_e32 v16, v16, v32
	v_mfma_f32_32x32x16_bf16 v[0:15], v[44:47], v[34:37], v[0:15]
	v_mul_f32_e32 v20, v48, v20
	v_exp_f32_e32 v34, v20
	v_add_f32_e32 v20, v21, v32
	v_exp_f32_e32 v20, v20
	v_add_f32_e32 v18, 1.0, v18
	v_fma_f32 v21, -v34, v34, 1.0
	v_max_f32_e32 v21, 0xda24260, v21
	v_add_f32_e32 v20, 1.0, v20
	s_nop 3
	v_add_f32_e32 v4, v4, v33
	v_rcp_f32_e32 v20, v20
	v_exp_f32_e32 v4, v4
	v_add_f32_e32 v5, v5, v33
	v_exp_f32_e32 v5, v5
	v_mul_f32_e32 v20, v48, v20
	v_add_f32_e32 v4, 1.0, v4
	v_exp_f32_e32 v36, v20
	v_mul_f32_e32 v35, v4, v21
	v_mul_f32_e32 v4, v4, v35
	v_rsq_f32_e32 v4, v4
	v_fma_f32 v20, -v36, v36, 1.0
	v_add_f32_e32 v5, 1.0, v5
	v_max_f32_e32 v20, 0xda24260, v20
	v_mul_f32_e32 v35, v5, v20
	v_mul_f32_e32 v5, v5, v35
	v_mul_f32_e32 v35, v21, v4
	v_add_f32_e32 v4, 1.0, v22
	v_rcp_f32_e32 v4, v4
	v_rsq_f32_e32 v5, v5
	v_add_f32_e32 v7, v7, v33
	v_exp_f32_e32 v7, v7
	v_mul_f32_e32 v4, v48, v4
	v_exp_f32_e32 v37, v4
	v_add_f32_e32 v4, v23, v32
	v_exp_f32_e32 v4, v4
	v_mul_f32_e32 v22, v20, v5
	v_add_f32_e32 v5, v6, v33
	v_exp_f32_e32 v5, v5
	v_add_f32_e32 v4, 1.0, v4
	v_rcp_f32_e32 v4, v4
	v_fma_f32 v6, -v37, v37, 1.0
	v_add_f32_e32 v5, 1.0, v5
	v_max_f32_e32 v6, 0xda24260, v6
	v_mul_f32_e32 v4, v48, v4
	v_exp_f32_e32 v23, v4
	v_mul_f32_e32 v20, v5, v6
	v_mul_f32_e32 v4, v5, v20
	v_add_f32_e32 v20, v24, v32
	v_rsq_f32_e32 v5, v4
; template <int PASS>
; __device__ __forceinline__ void lru_item(Frame& F, const LAS bf16* lw, const LAS float* prm, const LAS float* cwl, LAS float* xs, LAS unsigned char* pf, int head, int item, int nitem) {
;     ...
;                 const float br = prm[(d * 3 + 0) * 64 + chl], bi = prm[(d * 3 + 1) * 64 + chl], c8 = prm[(d * 3 + 2) * 64 + chl];
; #pragma unroll
;                 for (int rg = 0; rg < 16; ++rg) {
;                     const float rr = __builtin_amdgcn_rcpf(1.f + __builtin_amdgcn_exp2f(acc[0][rg] + br)), ei = 1.f + __builtin_amdgcn_exp2f(acc[1][rg] + bi);
;                     const float a = __builtin_amdgcn_exp2f(c8 * rr), om = fmaxf(fmaf(-a, a, 1.f), 1e-30f);
;                     av[rg] = a; bv[rg] = (om * __builtin_amdgcn_rsqf(om * ei * ei)) * xd[ct][rg];
;                 }
;             }
;             float hl[16], cp[16], sA[4], sB[4];
; #pragma unroll
;             for (int q4 = 0; q4 < 4; ++q4) {
;                 if (d == 0) {
;                     hl[4 * q4] = bv[4 * q4]; cp[4 * q4] = av[4 * q4];
; #pragma unroll
;                     for (int i = 1; i < 4; ++i) { hl[4 * q4 + i] = av[4 * q4 + i] * hl[4 * q4 + i - 1] + bv[4 * q4 + i]; cp[4 * q4 + i] = av[4 * q4 + i] * cp[4 * q4 + i - 1]; }
;                     sA[q4] = cp[4 * q4 + 3]; sB[q4] = hl[4 * q4 + 3];
;                 } else {
;                     hl[4 * q4 + 3] = bv[4 * q4 + 3]; cp[4 * q4 + 3] = av[4 * q4 + 3];
; #pragma unroll
;                     for (int i = 2; i >= 0; --i) { hl[4 * q4 + i] = av[4 * q4 + i] * hl[4 * q4 + i + 1] + bv[4 * q4 + i]; cp[4 * q4 + i] = av[4 * q4 + i] * cp[4 * q4 + i + 1]; }
;                     sA[q4] = cp[4 * q4]; sB[q4] = hl[4 * q4];
;                 }
;             }
;             float Ae[4], Be[4], Ao[4], Bo[4];
; #pragma unroll
;             for (int q4 = 0; q4 < 4; ++q4) {
;                 const float oA = shx(sA[q4], 32, lane), oB = shx(sB[q4], 32, lane);
;                 Ae[q4] = hh ? oA : sA[q4]; Be[q4] = hh ? oB : sB[q4]; Ao[q4] = hh ? sA[q4] : oA; Bo[q4] = hh ? sB[q4] : oB;
;             }
;             if (PASS == 1) {
;                 float c = 0.f, P = 1.f;
;                 if (d == 0) {
; #pragma unroll
;                     for (int q4 = 0; q4 < 4; ++q4) { c = Ae[q4] * c + Be[q4]; c = Ao[q4] * c + Bo[q4]; P *= Ae[q4] * Ao[q4]; } }
;                 else {
; #pragma unroll
	v_add_f32_e32 v4, 1.0, v7
	v_fma_f32 v7, -v23, v23, 1.0
	v_exp_f32_e32 v20, v20
	v_max_f32_e32 v7, 0xda24260, v7
	v_mul_f32_e32 v21, v4, v7
	v_mul_f32_e32 v4, v4, v21
	v_add_f32_e32 v20, 1.0, v20
	v_rsq_f32_e32 v21, v4
	v_add_f32_e32 v4, v8, v33
	v_rcp_f32_e32 v20, v20
	v_exp_f32_e32 v8, v4
	v_mul_f32_e32 v24, v6, v5
	v_mul_f32_e32 v5, v7, v21
	v_mul_f32_e32 v4, v48, v20
	v_add_f32_e32 v6, 1.0, v8
	v_add_f32_e32 v8, v25, v32
	v_exp_f32_e32 v4, v4
	v_exp_f32_e32 v8, v8
	v_mul_f32_e32 v25, v79, v5
	v_add_f32_e32 v11, v11, v33
	v_fma_f32 v7, -v4, v4, 1.0
	v_add_f32_e32 v8, 1.0, v8
	v_max_f32_e32 v7, 0xda24260, v7
	v_rcp_f32_e32 v8, v8
	v_mul_f32_e32 v20, v6, v7
	v_mul_f32_e32 v6, v6, v20
	v_rsq_f32_e32 v20, v6
	v_add_f32_e32 v6, v9, v33
	v_exp_f32_e32 v9, v6
	v_mul_f32_e32 v6, v48, v8
	v_exp_f32_e32 v6, v6
	v_add_f32_e32 v8, v26, v32
	v_exp_f32_e32 v8, v8
	v_mul_f32_e32 v38, v7, v20
	v_fma_f32 v7, -v6, v6, 1.0
	v_add_f32_e32 v5, 1.0, v9
	v_max_f32_e32 v7, 0xda24260, v7
	v_mul_f32_e32 v9, v5, v7
	v_mul_f32_e32 v5, v5, v9
	v_add_f32_e32 v8, 1.0, v8
	v_add_f32_e32 v9, v10, v33
	v_add_f32_e32 v10, v27, v32
	v_rcp_f32_e32 v8, v8
	v_exp_f32_e32 v10, v10
	v_exp_f32_e32 v9, v9
	v_exp_f32_e32 v11, v11
	v_mul_f32_e32 v8, v48, v8
	v_add_f32_e32 v10, 1.0, v10
	v_exp_f32_e32 v8, v8
	v_rcp_f32_e32 v10, v10
	v_add_f32_e32 v9, 1.0, v9
	v_rsq_f32_e32 v5, v5
	v_fma_f32 v20, -v8, v8, 1.0
	v_mul_f32_e32 v10, v48, v10
	v_max_f32_e32 v21, 0xda24260, v20
	v_exp_f32_e32 v20, v10
	v_add_f32_e32 v10, 1.0, v11
	v_mul_f32_e32 v26, v9, v21
	v_mul_f32_e32 v9, v9, v26
	v_fma_f32 v11, -v20, v20, 1.0
	v_max_f32_e32 v11, 0xda24260, v11
	v_mul_f32_e32 v26, v10, v11
	v_mul_f32_e32 v10, v10, v26
	v_add_f32_e32 v26, v28, v32
	v_exp_f32_e32 v26, v26
	v_rsq_f32_e32 v10, v10
	v_mul_f32_e32 v27, v7, v5
	v_rsq_f32_e32 v9, v9
	v_add_f32_e32 v7, 1.0, v26
	v_rcp_f32_e32 v7, v7
	v_mul_f32_e32 v5, v11, v10
	v_mul_f32_e32 v26, v77, v5
	v_add_f32_e32 v5, v12, v33
	v_mul_f32_e32 v28, v21, v9
	v_exp_f32_e32 v9, v5
	v_mul_f32_e32 v5, v48, v7
	v_add_f32_e32 v7, v29, v32
	v_exp_f32_e32 v7, v7
	v_exp_f32_e32 v5, v5
	v_add_f32_e32 v12, v13, v33
	v_exp_f32_e32 v12, v12
	v_add_f32_e32 v7, 1.0, v7
	v_rcp_f32_e32 v7, v7
	v_fma_f32 v10, -v5, v5, 1.0
	v_add_f32_e32 v9, 1.0, v9
	v_max_f32_e32 v10, 0xda24260, v10
	v_mul_f32_e32 v7, v48, v7
	v_exp_f32_e32 v7, v7
	v_mul_f32_e32 v11, v9, v10
	v_add_f32_e32 v13, v30, v32
	v_mul_f32_e32 v9, v9, v11
	v_exp_f32_e32 v13, v13
	v_rsq_f32_e32 v11, v9
	v_add_f32_e32 v9, 1.0, v12
	v_fma_f32 v12, -v7, v7, 1.0
	v_max_f32_e32 v12, 0xda24260, v12
	v_mul_f32_e32 v21, v9, v12
	v_mul_f32_e32 v9, v9, v21
	v_add_f32_e32 v13, 1.0, v13
	v_rcp_f32_e32 v13, v13
	v_rsq_f32_e32 v21, v9
	v_add_f32_e32 v9, v14, v33
	v_exp_f32_e32 v14, v9
	v_mul_f32_e32 v9, v48, v13
	v_mul_f32_e32 v13, v12, v21
	v_add_f32_e32 v12, v31, v32
	v_exp_f32_e32 v12, v12
	v_exp_f32_e32 v9, v9
	v_mul_f32_e32 v29, v10, v11
	v_add_f32_e32 v10, 1.0, v14
	v_add_f32_e32 v12, 1.0, v12
	v_rcp_f32_e32 v12, v12
	v_fma_f32 v11, -v9, v9, 1.0
	v_max_f32_e32 v11, 0xda24260, v11
	v_mul_f32_e32 v14, v10, v11
	v_mul_f32_e32 v10, v10, v14
	v_mul_f32_e32 v12, v48, v12
	v_rsq_f32_e32 v10, v10
	v_add_f32_e32 v14, v15, v33
	v_exp_f32_e32 v21, v12
	v_exp_f32_e32 v14, v14
	v_add_f32_e32 v12, v19, v32
	v_exp_f32_e32 v12, v12
	v_mul_f32_e32 v15, v11, v10
	v_fma_f32 v11, -v21, v21, 1.0
	v_add_f32_e32 v10, 1.0, v14
	v_max_f32_e32 v11, 0xda24260, v11
	v_add_f32_e32 v12, 1.0, v12
	v_mul_f32_e32 v14, v10, v11
	v_rcp_f32_e32 v12, v12
	v_mul_f32_e32 v10, v10, v14
	v_rsq_f32_e32 v10, v10
	v_add_f32_e32 v3, v3, v33
	v_mul_f32_e32 v12, v48, v12
	v_exp_f32_e32 v12, v12
	v_mul_f32_e32 v10, v11, v10
	v_add_f32_e32 v11, v17, v32
	v_exp_f32_e32 v3, v3
	v_exp_f32_e32 v11, v11
	v_rcp_f32_e32 v18, v18
	v_fma_f32 v14, -v12, v12, 1.0
	v_exp_f32_e32 v16, v16
	v_max_f32_e32 v14, 0xda24260, v14
	v_add_f32_e32 v3, 1.0, v3
	v_add_f32_e32 v11, 1.0, v11
	v_mul_f32_e32 v19, v3, v14
	v_rcp_f32_e32 v11, v11
	v_mul_f32_e32 v3, v3, v19
	v_mul_f32_e32 v19, v75, v10
	v_mul_f32_e32 v10, v48, v18
	v_rsq_f32_e32 v3, v3
	v_exp_f32_e32 v10, v10
	v_add_f32_e32 v2, v2, v33
	v_add_f32_e32 v16, 1.0, v16
	v_exp_f32_e32 v2, v2
	v_rcp_f32_e32 v16, v16
	v_mul_f32_e32 v11, v48, v11
	v_exp_f32_e32 v11, v11
	v_add_f32_e32 v1, v1, v33
	v_mul_f32_e32 v3, v14, v3
	v_fma_f32 v14, -v10, v10, 1.0
	v_exp_f32_e32 v1, v1
	v_max_f32_e32 v14, 0xda24260, v14
	v_add_f32_e32 v2, 1.0, v2
	v_mul_f32_e32 v16, v48, v16
	v_mul_f32_e32 v17, v2, v14
	v_exp_f32_e32 v16, v16
	v_add_f32_e32 v0, v0, v33
	v_mul_f32_e32 v2, v2, v17
	v_fma_f32 v17, -v11, v11, 1.0
	v_exp_f32_e32 v0, v0
	v_max_f32_e32 v17, 0xda24260, v17
	v_add_f32_e32 v1, 1.0, v1
	v_mul_f32_e32 v18, v1, v17
	v_rsq_f32_e32 v2, v2
	v_mul_f32_e32 v1, v1, v18
	v_fma_f32 v18, -v16, v16, 1.0
	v_max_f32_e32 v18, 0xda24260, v18
	v_add_f32_e32 v0, 1.0, v0
	v_rsq_f32_e32 v1, v1
	v_mul_f32_e32 v30, v0, v18
	v_mul_f32_e32 v0, v0, v30
	v_mul_f32_e32 v3, v73, v3
	v_rsq_f32_e32 v0, v0
	v_mul_f32_e32 v2, v14, v2
	v_mul_f32_e32 v3, v10, v3
	v_fmac_f32_e32 v3, v69, v2
	v_mul_f32_e32 v1, v17, v1
	v_mul_f32_e32 v3, v11, v3
	v_fmac_f32_e32 v3, v65, v1
	v_mul_f32_e32 v0, v18, v0
	v_mul_f32_e32 v1, v16, v3
	v_fmac_f32_e32 v1, v59, v0
	v_mul_f32_e32 v0, v37, v25
	v_fmac_f32_e32 v0, v67, v24
	v_mul_f32_e32 v0, v36, v0
	v_fmac_f32_e32 v0, v61, v22
	v_mul_f32_e32 v2, v12, v10
	v_mul_f32_e32 v10, v34, v0
	v_mul_f32_e32 v0, v8, v26
	v_fmac_f32_e32 v0, v63, v28
	v_mul_f32_e32 v0, v6, v0
	v_fmac_f32_e32 v0, v57, v27
	v_mul_f32_e32 v12, v4, v0
	v_mul_f32_e32 v0, v9, v19
	v_fmac_f32_e32 v0, v71, v15
	v_mul_f32_e32 v2, v11, v2
	v_mul_f32_e32 v0, v7, v0
	v_mul_f32_e32 v3, v16, v2
	v_mul_f32_e32 v2, v23, v37
	v_fmac_f32_e32 v0, v55, v13
	v_pk_mul_f32 v[8:9], v[20:21], v[8:9]
	v_mul_f32_e32 v2, v36, v2
	v_mul_f32_e32 v13, v5, v0
	v_pk_mul_f32 v[6:7], v[6:7], v[8:9]
	v_fmac_f32_e32 v10, v51, v35
	v_mul_f32_e32 v11, v34, v2
	v_fmac_f32_e32 v12, v53, v38
	v_fmac_f32_e32 v13, v49, v29
	v_pk_mul_f32 v[6:7], v[4:5], v[6:7]
	s_nop 1
	v_permlane32_swap_b32 v3, v4
	v_permlane32_swap_b32 v1, v5
	v_permlane32_swap_b32 v11, v15
	v_permlane32_swap_b32 v10, v14
	v_permlane32_swap_b32 v6, v8
	v_permlane32_swap_b32 v12, v16
	v_permlane32_swap_b32 v7, v9
	v_permlane32_swap_b32 v13, v17
	s_and_saveexec_b64 s[10:11], vcc
	s_cbranch_execz .LBB0_693
	s_waitcnt lgkmcnt(0)
	v_fmac_f32_e32 v17, 0, v9
	v_fmac_f32_e32 v13, v7, v17
	v_fmac_f32_e32 v16, v13, v8
	v_fmac_f32_e32 v12, v6, v16
	v_pk_mul_f32 v[18:19], v[6:7], v[8:9]
	v_fmac_f32_e32 v14, v12, v15
	v_mul_f32_e32 v2, v11, v15
	v_fmac_f32_e32 v10, v11, v14
	v_pk_mul_f32 v[6:7], v[18:19], v[18:19] op_sel:[0,1] op_sel_hi:[1,0]
	v_mul_f32_e32 v0, v3, v4
	v_fmac_f32_e32 v5, v10, v4
	s_lshl_b64 s[8:9], s[8:9], 2
	v_mov_b32_e32 v4, v6
	v_pk_mul_f32 v[6:7], v[2:3], v[6:7]
	s_add_u32 s8, s19, s8
	v_pk_mul_f32 v[6:7], v[0:1], v[6:7]
	v_pk_fma_f32 v[0:1], v[2:3], v[4:5], v[0:1]
	s_addc_u32 s9, s30, s9
	v_mov_b32_e32 v7, v1
	global_store_dwordx2 v84, v[6:7], s[8:9]
	s_branch .LBB0_693
